# reto (retention output) item-start waits: counted vmcnt instead of vmcnt(0), no longer waits for the previous item's stores before issuing loads
# baseline (speedup 1.0000x reference)
.LBB0_34:
	s_load_dwordx2 s[20:21], s[36:37], 0x58
	s_waitcnt lgkmcnt(0)
	v_readlane_b32 s28, v255, 14
	v_readlane_b32 s29, v255, 15
	s_mov_b32 s48, s28
	s_lshl_b32 s28, s28, 8
	s_ashr_i32 s29, s28, 31
	s_lshl_b64 s[28:29], s[28:29], 2
	s_add_u32 s44, s20, s28
	s_addc_u32 s45, s21, s29
	s_lshl_b32 s20, s48, 3
	s_ashr_i32 s21, s20, 31
	s_lshl_b64 s[20:21], s[20:21], 2
	s_add_u32 s28, s46, s20
	v_bfe_u32 v0, v140, 4, 2
	s_addc_u32 s29, s47, s21
	s_ashr_i32 s16, s16, 2
	v_lshlrev_b32_e32 v52, 3, v0
	v_lshlrev_b32_e32 v152, 2, v0
	v_lshl_add_u32 v164, v0, 4, 0
	v_lshlrev_b32_e32 v0, 3, v140
	v_bfi_b32 v134, -16, s16, v140
	v_and_b32_e32 v0, 24, v0
	v_add_u32_e32 v220, 0, v0
	v_add_u32_e32 v0, 1, v134
	v_cvt_f32_i32_e32 v139, v0
	v_sub_u32_e32 v0, 0x80, v134
	v_and_b32_e32 v163, 15, v140
	v_cvt_f32_i32_e32 v141, v0
	v_lshl_or_b32 v53, v163, 6, v52
	v_mul_lo_u32 v54, v166, s65
	v_bfe_u32 v51, v140, 2, 2
	v_add_u32_e32 v54, 0, v54
	v_lshlrev_b32_e32 v50, 5, v50
	v_lshlrev_b32_e32 v159, 1, v53
	v_ashrrev_i32_e32 v135, 31, v134
	v_or_b32_e32 v219, v152, v51
	s_andn2_b64 vcc, exec, s[2:3]
	v_add_u32_e32 v153, v54, v50
	v_lshlrev_b32_e32 v136, 1, v52
	v_or_b32_e32 v162, 64, v159
	v_or_b32_e32 v161, 0x800, v159
	v_or_b32_e32 v160, 0x840, v159
	v_or_b32_e32 v158, 0x1000, v159
	v_or_b32_e32 v157, 0x1040, v159
	v_or_b32_e32 v156, 0x1800, v159
	v_or_b32_e32 v155, 0x1840, v159
	v_or_b32_e32 v154, s40, v152
	s_cbranch_vccnz .LBB0_38
	v_readlane_b32 s2, v253, 5
	v_readlane_b32 s3, v253, 6
	v_mov_b64_e32 v[50:51], s[72:73]
	s_lshl_b32 s16, s40, 1
	v_lshl_add_u64 v[142:143], s[2:3], 0, v[134:135]
	v_readlane_b32 s2, v253, 7
	s_lshl_b32 s2, s2, 2
	v_mov_b32_e32 v137, v1
	v_mov_b32_e32 v0, s2
	v_mad_u64_u32 v[50:51], s[2:3], v142, s64, v[50:51]
	v_mad_i32_i24 v51, v143, s64, v51
	v_lshl_add_u64 v[52:53], v[50:51], 0, s[16:17]
	v_lshl_add_u64 v[52:53], v[52:53], 0, v[136:137]
	global_load_dword v168, v0, s[28:29]
	global_load_dword v167, v0, s[28:29] offset:16
	global_load_dwordx4 v[118:121], v[52:53], off
	global_load_dwordx4 v[98:101], v[52:53], off offset:64
	v_readlane_b32 s2, v253, 9
	v_readlane_b32 s3, v253, 10
	s_add_u32 s2, s42, s2
	s_addc_u32 s3, s43, s3
	v_lshlrev_b32_e32 v0, 1, v154
	s_add_u32 s20, s2, 0x2000
	v_lshl_add_u64 v[50:51], v[50:51], 0, v[0:1]
	v_lshlrev_b32_e32 v52, 2, v154
	s_addc_u32 s21, s3, 0
	global_load_dwordx4 v[66:69], v159, s[2:3]
	global_load_dwordx4 v[70:73], v159, s[20:21]
	global_load_dwordx4 v[74:77], v159, s[2:3] offset:64
	global_load_dwordx4 v[78:81], v162, s[20:21]
	global_load_dwordx4 v[82:85], v159, s[2:3] offset:2048
	global_load_dwordx4 v[86:89], v161, s[20:21]
	global_load_dwordx4 v[94:97], v159, s[2:3] offset:2112
	global_load_dwordx4 v[106:109], v160, s[20:21]
	global_load_dwordx4 v[110:113], v158, s[2:3]
	global_load_dwordx4 v[114:117], v158, s[20:21]
	global_load_dwordx4 v[122:125], v157, s[2:3]
	global_load_dwordx4 v[126:129], v157, s[20:21]
	global_load_dwordx4 v[130:133], v156, s[2:3]
	global_load_dwordx4 v[170:173], v156, s[20:21]
	global_load_dwordx4 v[90:93], v155, s[2:3]
	global_load_dwordx4 v[102:105], v155, s[20:21]
	global_load_dwordx2 v[150:151], v[50:51], off offset:1536
	global_load_dwordx4 v[62:65], v52, s[44:45]
	global_load_dwordx2 v[148:149], v[50:51], off offset:1568
	global_load_dwordx4 v[58:61], v52, s[44:45] offset:64
	global_load_dwordx2 v[146:147], v[50:51], off offset:1600
	global_load_dwordx4 v[54:57], v52, s[44:45] offset:128
	global_load_dwordx2 v[144:145], v[50:51], off offset:1632
	s_nop 0
	global_load_dwordx4 v[50:53], v52, s[44:45] offset:192
	v_readlane_b32 s2, v253, 31
	s_cmp_ge_i32 s2, s15
	s_waitcnt vmcnt(28)
	ds_write_b128 v153, v[22:25]
	ds_write_b128 v153, v[18:21] offset:16
	s_waitcnt vmcnt(28)
	ds_write_b128 v153, v[30:33] offset:18432
	ds_write_b128 v153, v[26:29] offset:18448
	s_waitcnt lgkmcnt(0)
	s_barrier
	s_waitcnt vmcnt(23)
	v_mfma_f32_16x16x32_bf16 v[66:69], v[66:69], v[118:121], 0
	s_waitcnt vmcnt(22)
	v_mfma_f32_16x16x32_bf16 v[194:197], v[70:73], v[118:121], 0
	s_waitcnt vmcnt(21)
	v_mfma_f32_16x16x32_bf16 v[70:73], v[74:77], v[98:101], v[66:69]
	s_waitcnt vmcnt(19)
	v_mfma_f32_16x16x32_bf16 v[74:77], v[82:85], v[118:121], 0
	s_waitcnt vmcnt(18)
	v_mfma_f32_16x16x32_bf16 v[82:85], v[86:89], v[118:121], 0
	v_mfma_f32_16x16x32_bf16 v[66:69], v[78:81], v[98:101], v[194:197]
	s_waitcnt vmcnt(17)
	v_mfma_f32_16x16x32_bf16 v[78:81], v[94:97], v[98:101], v[74:77]
	s_waitcnt vmcnt(16)
	v_mfma_f32_16x16x32_bf16 v[74:77], v[106:109], v[98:101], v[82:85]
	s_waitcnt vmcnt(15)
	v_mfma_f32_16x16x32_bf16 v[82:85], v[110:113], v[118:121], 0
	s_waitcnt vmcnt(14)
	v_mfma_f32_16x16x32_bf16 v[94:97], v[114:117], v[118:121], 0
	s_waitcnt vmcnt(13)
	v_mfma_f32_16x16x32_bf16 v[86:89], v[122:125], v[98:101], v[82:85]
	s_waitcnt vmcnt(12)
	v_mfma_f32_16x16x32_bf16 v[82:85], v[126:129], v[98:101], v[94:97]
	s_waitcnt vmcnt(11)
	v_mfma_f32_16x16x32_bf16 v[94:97], v[130:133], v[118:121], 0
	s_waitcnt vmcnt(10)
	v_mfma_f32_16x16x32_bf16 v[106:109], v[170:173], v[118:121], 0
	s_waitcnt vmcnt(9)
	v_mfma_f32_16x16x32_bf16 v[94:97], v[90:93], v[98:101], v[94:97]
	s_waitcnt vmcnt(8)
	v_mfma_f32_16x16x32_bf16 v[90:93], v[102:105], v[98:101], v[106:109]
	s_cbranch_scc1 .LBB0_37
	v_readlane_b32 s2, v253, 11
	v_mov_b64_e32 v[18:19], s[72:73]
	v_mov_b32_e32 v21, v1
	v_add_u32_e32 v20, s2, v166
	v_mad_i64_i32 v[18:19], s[2:3], v20, s64, v[18:19]
	v_readlane_b32 s2, v254, 48
	v_readlane_b32 s3, v254, 49
	s_mov_b32 s3, s17
	v_lshlrev_b32_e32 v20, 1, v165
	v_lshl_add_u64 v[18:19], v[18:19], 0, s[2:3]
	v_lshl_add_u64 v[30:31], v[18:19], 0, v[20:21]
	global_load_dwordx4 v[18:21], v[30:31], off offset:528
	global_load_dwordx4 v[22:25], v[30:31], off offset:512
	global_load_dwordx4 v[26:29], v[30:31], off offset:1040
	s_nop 0
	global_load_dwordx4 v[30:33], v[30:31], off offset:1024
	s_mov_b32 s16, s2
	v_writelane_b32 v254, s16, 48
	s_nop 1
	v_writelane_b32 v254, s17, 49

.LBB0_38:
	s_andn2_b64 vcc, exec, s[22:23]
	s_cbranch_vccnz .LBB0_42
	v_readlane_b32 s2, v253, 12
	v_readlane_b32 s3, v253, 13
	v_mov_b64_e32 v[50:51], s[72:73]
	v_readlane_b32 s22, v253, 14
	v_lshl_add_u64 v[142:143], s[2:3], 0, v[134:135]
	v_mad_u64_u32 v[114:115], s[2:3], v142, s64, v[50:51]
	s_lshl_b32 s16, s22, 1
	v_readlane_b32 s2, v253, 15
	v_mad_i32_i24 v115, v143, s64, v115
	v_readlane_b32 s3, v253, 16
	s_add_u32 s2, s42, s2
	s_addc_u32 s3, s43, s3
	v_lshl_add_u64 v[54:55], v[114:115], 0, s[16:17]
	v_mov_b32_e32 v137, v1
	v_lshl_add_u64 v[110:111], v[54:55], 0, v[136:137]
	s_add_u32 s20, s2, 0x2000
	global_load_dwordx4 v[50:53], v159, s[2:3]
	global_load_dwordx4 v[98:101], v[110:111], off
	v_readlane_b32 s16, v254, 35
	s_addc_u32 s21, s3, 0
	v_or_b32_e32 v119, s22, v152
	v_mov_b32_e32 v118, s16
	global_load_dwordx4 v[54:57], v159, s[2:3] offset:2048
	global_load_dwordx4 v[58:61], v159, s[2:3] offset:64
	global_load_dword v137, v118, s[28:29] offset:16
	global_load_dwordx4 v[62:65], v158, s[2:3]
	global_load_dwordx4 v[66:69], v159, s[2:3] offset:2112
	global_load_dwordx4 v[70:73], v158, s[20:21]
	global_load_dwordx4 v[74:77], v156, s[2:3]
	global_load_dwordx4 v[78:81], v156, s[20:21]
	v_lshlrev_b32_e32 v0, 1, v119
	v_lshl_add_u64 v[122:123], v[114:115], 0, v[0:1]
	s_waitcnt vmcnt(7)
	v_mfma_f32_16x16x32_bf16 v[54:57], v[54:57], v[98:101], 0
	s_waitcnt vmcnt(1)
	v_mfma_f32_16x16x32_bf16 v[82:85], v[74:77], v[98:101], 0
	global_load_dwordx4 v[74:77], v159, s[20:21]
	global_load_dwordx4 v[86:89], v162, s[20:21]
	v_mfma_f32_16x16x32_bf16 v[50:53], v[50:53], v[98:101], 0
	v_mfma_f32_16x16x32_bf16 v[62:65], v[62:65], v[98:101], 0
	v_mfma_f32_16x16x32_bf16 v[106:109], v[70:73], v[98:101], 0
	s_waitcnt vmcnt(1)
	v_mfma_f32_16x16x32_bf16 v[90:93], v[74:77], v[98:101], 0
	global_load_dwordx4 v[74:77], v161, s[20:21]
	global_load_dwordx4 v[94:97], v160, s[20:21]
	global_load_dwordx4 v[130:133], v[110:111], off offset:64
	global_load_dwordx2 v[148:149], v[122:123], off offset:1536
	v_mfma_f32_16x16x32_bf16 v[110:113], v[78:81], v[98:101], 0
	s_waitcnt vmcnt(3)
	v_mfma_f32_16x16x32_bf16 v[102:105], v[74:77], v[98:101], 0
	s_waitcnt vmcnt(1)
	v_mfma_f32_16x16x32_bf16 v[78:81], v[58:61], v[130:133], v[50:53]
	s_nop 2
	global_load_dwordx4 v[50:53], v157, s[2:3]
	v_mfma_f32_16x16x32_bf16 v[74:77], v[66:69], v[130:133], v[54:57]
	s_nop 2
	global_load_dwordx4 v[54:57], v155, s[2:3]
	global_load_dwordx4 v[114:117], v157, s[20:21]
	global_load_dword v167, v118, s[28:29]
	v_readlane_b32 s2, v253, 19
	v_mfma_f32_16x16x32_bf16 v[90:93], v[86:89], v[130:133], v[90:93]
	s_cmp_ge_i32 s2, s15
	v_mfma_f32_16x16x32_bf16 v[94:97], v[94:97], v[130:133], v[102:105]
	s_waitcnt vmcnt(2)
	v_mfma_f32_16x16x32_bf16 v[66:69], v[54:57], v[130:133], v[82:85]
	v_mfma_f32_16x16x32_bf16 v[70:73], v[50:53], v[130:133], v[62:65]
	v_lshlrev_b32_e32 v50, 2, v119
	global_load_dwordx4 v[118:121], v155, s[20:21]
	s_nop 0
	global_load_dwordx4 v[62:65], v50, s[44:45]
	global_load_dwordx4 v[58:61], v50, s[44:45] offset:64
	global_load_dwordx4 v[54:57], v50, s[44:45] offset:128
	s_nop 0
	global_load_dwordx4 v[50:53], v50, s[44:45] offset:192
	s_nop 0
	global_load_dwordx2 v[150:151], v[122:123], off offset:1568
	global_load_dwordx2 v[146:147], v[122:123], off offset:1600
	global_load_dwordx2 v[144:145], v[122:123], off offset:1632
	s_waitcnt vmcnt(9)
	v_mfma_f32_16x16x32_bf16 v[82:85], v[114:117], v[130:133], v[106:109]
	ds_write_b128 v153, v[6:9]
	ds_write_b128 v153, v[2:5] offset:16
	ds_write_b128 v153, v[14:17] offset:18432
	ds_write_b128 v153, v[10:13] offset:18448
	s_waitcnt lgkmcnt(0)
	s_barrier
	s_waitcnt vmcnt(7)
	v_mfma_f32_16x16x32_bf16 v[86:89], v[118:121], v[130:133], v[110:113]
	s_cbranch_scc1 .LBB0_41
	v_readlane_b32 s2, v253, 18
	v_mov_b64_e32 v[2:3], s[72:73]
	v_mov_b32_e32 v5, v1
	v_add_u32_e32 v4, s2, v166
	v_mad_i64_i32 v[2:3], s[2:3], v4, s64, v[2:3]
	v_readlane_b32 s2, v254, 50
	v_readlane_b32 s3, v254, 51
	s_mov_b32 s3, s17
	v_lshlrev_b32_e32 v4, 1, v165
	v_lshl_add_u64 v[2:3], v[2:3], 0, s[2:3]
	v_lshl_add_u64 v[14:15], v[2:3], 0, v[4:5]
	global_load_dwordx4 v[2:5], v[14:15], off offset:528
	global_load_dwordx4 v[6:9], v[14:15], off offset:512
	global_load_dwordx4 v[10:13], v[14:15], off offset:1040
	s_nop 0
	global_load_dwordx4 v[14:17], v[14:15], off offset:1024
	s_mov_b32 s16, s2
	v_writelane_b32 v254, s16, 50
	s_nop 1
	v_writelane_b32 v254, s17, 51

.LBB0_42:
	v_or_b32_e32 v194, 35, v152
	s_andn2_b64 vcc, exec, s[10:11]
	v_cmp_ne_u32_e64 s[10:11], v134, v194
	v_or_b32_e32 v175, 48, v152
	v_or_b32_e32 v173, 49, v152
	v_writelane_b32 v255, s10, 28
	v_or_b32_e32 v171, 50, v152
	v_or_b32_e32 v169, 51, v152
	v_writelane_b32 v255, s11, 29
	v_cmp_ne_u32_e64 s[10:11], v134, v175
	v_or_b32_e32 v167, 64, v152
	v_mad_u32_u24 v218, v163, s65, v164
	v_writelane_b32 v255, s10, 32
	v_or_b32_e32 v164, 0x41, v152
	v_or_b32_e32 v163, 0x42, v152
	v_writelane_b32 v255, s11, 33
	v_cmp_ne_u32_e64 s[10:11], v134, v173
	v_or_b32_e32 v214, 1, v152
	v_or_b32_e32 v212, 2, v152
	v_writelane_b32 v255, s10, 30
	v_or_b32_e32 v210, 3, v152
	v_or_b32_e32 v208, 16, v152
	v_writelane_b32 v255, s11, 31
	v_cmp_ne_u32_e64 s[10:11], v134, v171
	v_or_b32_e32 v206, 17, v152
	v_or_b32_e32 v204, 18, v152
	v_writelane_b32 v255, s10, 36
	v_or_b32_e32 v202, 19, v152
	v_or_b32_e32 v200, 32, v152
	v_writelane_b32 v255, s11, 37
	v_cmp_ne_u32_e64 s[10:11], v134, v169
	v_or_b32_e32 v198, 33, v152
	v_or_b32_e32 v196, 34, v152
	v_writelane_b32 v255, s10, 34
	v_or_b32_e32 v149, 0x43, v152
	v_or_b32_e32 v148, 0x50, v152
	v_writelane_b32 v255, s11, 35
	v_cmp_ne_u32_e64 s[10:11], v134, v167
	v_or_b32_e32 v146, 0x51, v152
	v_sub_u32_e32 v217, v134, v152
	v_writelane_b32 v255, s10, 24
	v_cmp_ne_u32_e64 s[82:83], v134, v152
	v_sub_u32_e32 v216, v134, v214
	v_writelane_b32 v255, s11, 25
	v_cmp_ne_u32_e64 s[10:11], v134, v164
	v_cmp_ne_u32_e64 s[2:3], v134, v214
	v_sub_u32_e32 v215, v134, v212
	v_writelane_b32 v255, s10, 22
	v_cmp_ne_u32_e64 s[78:79], v134, v212
	v_sub_u32_e32 v213, v134, v210
	v_writelane_b32 v255, s11, 23
	v_cmp_ne_u32_e64 s[10:11], v134, v163
	v_cmp_ne_u32_e64 s[76:77], v134, v210
	v_sub_u32_e32 v211, v134, v208
	v_writelane_b32 v255, s10, 48
	v_cmp_ne_u32_e64 s[74:75], v134, v208
	v_sub_u32_e32 v209, v134, v206
	v_cmp_ne_u32_e64 s[40:41], v134, v206
	v_sub_u32_e32 v207, v134, v204
	v_cmp_ne_u32_e64 s[94:95], v134, v204
	v_sub_u32_e32 v205, v134, v202
	v_cmp_ne_u32_e64 s[52:53], v134, v202
	v_sub_u32_e32 v203, v134, v200
	v_cmp_ne_u32_e64 s[50:51], v134, v200
	v_sub_u32_e32 v201, v134, v198
	v_cmp_ne_u32_e64 s[48:49], v134, v198
	v_sub_u32_e32 v199, v134, v196
	v_cmp_ne_u32_e64 s[46:47], v134, v196
	v_sub_u32_e32 v197, v134, v194
	v_sub_u32_e32 v195, v134, v175
	v_sub_u32_e32 v193, v134, v173
	v_sub_u32_e32 v174, v134, v171
	v_sub_u32_e32 v172, v134, v169
	v_sub_u32_e32 v170, v134, v167
	v_sub_u32_e32 v168, v134, v164
	v_sub_u32_e32 v166, v134, v163
	v_writelane_b32 v255, s11, 49
	v_sub_u32_e32 v165, v134, v149
	v_cmp_ne_u32_e64 s[22:23], v134, v149
	v_sub_u32_e32 v151, v134, v148
	v_cmp_ne_u32_e64 s[20:21], v134, v148
	v_sub_u32_e32 v150, v134, v146
	v_cmp_ne_u32_e64 s[10:11], v134, v146
	v_or_b32_e32 v147, 0x52, v152
	v_or_b32_e32 v145, 0x53, v152
	v_or_b32_e32 v144, 0x60, v152
	v_or_b32_e32 v143, 0x61, v152
	v_or_b32_e32 v142, 0x62, v152
	v_or_b32_e32 v133, 0x63, v152
	v_or_b32_e32 v132, 0x70, v152
	v_or_b32_e32 v131, 0x71, v152
	v_or_b32_e32 v130, 0x72, v152
	v_or_b32_e32 v129, 0x73, v152
	v_mad_u32_u24 v128, v219, s65, v220
	s_cbranch_vccnz .LBB0_44
	v_writelane_b32 v255, s10, 40
	v_mov_b64_e32 v[50:51], s[72:73]
	v_mov_b32_e32 v137, v1
	v_writelane_b32 v255, s11, 41
	v_readlane_b32 s10, v253, 20
	v_readlane_b32 s11, v253, 21
	v_writelane_b32 v255, s22, 46
	v_cmp_gt_i32_e32 vcc, 0, v217
	v_lshl_add_u64 v[118:119], s[10:11], 0, v[134:135]
	v_readlane_b32 s10, v254, 36
	v_writelane_b32 v255, s23, 47
	v_readlane_b32 s22, v253, 22
	v_mov_b32_e32 v0, s10
	v_mad_u64_u32 v[50:51], s[10:11], v118, s64, v[50:51]
	v_mad_i32_i24 v51, v119, s64, v51
	s_lshl_b32 s16, s22, 1
	v_lshl_add_u64 v[52:53], v[50:51], 0, s[16:17]
	v_lshl_add_u64 v[52:53], v[52:53], 0, v[136:137]
	global_load_dword v220, v0, s[28:29]
	global_load_dword v219, v0, s[28:29] offset:16
	global_load_dwordx4 v[102:105], v[52:53], off
	global_load_dwordx4 v[82:85], v[52:53], off offset:64
	v_readlane_b32 s10, v253, 24
	v_readlane_b32 s11, v253, 25
	s_add_u32 s10, s42, s10
	s_addc_u32 s11, s43, s11
	v_writelane_b32 v255, s20, 52
	v_or_b32_e32 v52, s22, v152
	v_lshlrev_b32_e32 v0, 1, v52
	v_writelane_b32 v255, s21, 53
	s_add_u32 s20, s10, 0x2000
	s_addc_u32 s21, s11, 0
	global_load_dwordx4 v[66:69], v159, s[10:11]
	global_load_dwordx4 v[70:73], v159, s[20:21]
	global_load_dwordx4 v[86:89], v159, s[10:11] offset:64
	global_load_dwordx4 v[90:93], v162, s[20:21]
	global_load_dwordx4 v[94:97], v159, s[10:11] offset:2048
	global_load_dwordx4 v[98:101], v161, s[20:21]
	global_load_dwordx4 v[106:109], v159, s[10:11] offset:2112
	global_load_dwordx4 v[110:113], v160, s[20:21]
	global_load_dwordx4 v[114:117], v158, s[10:11]
	global_load_dwordx4 v[222:225], v158, s[20:21]
	global_load_dwordx4 v[226:229], v157, s[10:11]
	global_load_dwordx4 v[230:233], v157, s[20:21]
	global_load_dwordx4 v[234:237], v156, s[10:11]
	global_load_dwordx4 v[238:241], v156, s[20:21]
	global_load_dwordx4 v[74:77], v155, s[10:11]
	global_load_dwordx4 v[78:81], v155, s[20:21]
	v_lshl_add_u64 v[50:51], v[50:51], 0, v[0:1]
	v_lshlrev_b32_e32 v52, 2, v52
	global_load_dwordx2 v[126:127], v[50:51], off offset:1536
	global_load_dwordx4 v[62:65], v52, s[44:45]
	global_load_dwordx2 v[124:125], v[50:51], off offset:1568
	global_load_dwordx4 v[58:61], v52, s[44:45] offset:64
	global_load_dwordx2 v[122:123], v[50:51], off offset:1600
	global_load_dwordx4 v[54:57], v52, s[44:45] offset:128
	global_load_dwordx2 v[120:121], v[50:51], off offset:1632
	s_nop 0
	global_load_dwordx4 v[50:53], v52, s[44:45] offset:192
	s_waitcnt vmcnt(28)
	ds_write_b128 v153, v[46:49]
	ds_write_b128 v153, v[38:41] offset:16
	s_waitcnt vmcnt(28)
	ds_write_b128 v153, v[42:45] offset:18432
	ds_write_b128 v153, v[34:37] offset:18448
	s_waitcnt lgkmcnt(0)
	s_barrier
	s_waitcnt vmcnt(23)
	v_mfma_f32_16x16x32_bf16 v[34:37], v[66:69], v[102:105], 0
	s_waitcnt vmcnt(22)
	v_mfma_f32_16x16x32_bf16 v[42:45], v[70:73], v[102:105], 0
	s_waitcnt vmcnt(21)
	v_mfma_f32_16x16x32_bf16 v[38:41], v[86:89], v[82:85], v[34:37]
	s_waitcnt vmcnt(20)
	v_mfma_f32_16x16x32_bf16 v[34:37], v[90:93], v[82:85], v[42:45]
	s_waitcnt vmcnt(19)
	v_mfma_f32_16x16x32_bf16 v[42:45], v[94:97], v[102:105], 0
	s_waitcnt vmcnt(18)
	v_mfma_f32_16x16x32_bf16 v[66:69], v[98:101], v[102:105], 0
	s_waitcnt vmcnt(17)
	v_mfma_f32_16x16x32_bf16 v[46:49], v[106:109], v[82:85], v[42:45]
	s_waitcnt vmcnt(16)
	v_mfma_f32_16x16x32_bf16 v[42:45], v[110:113], v[82:85], v[66:69]
	s_waitcnt vmcnt(15)
	v_mfma_f32_16x16x32_bf16 v[66:69], v[114:117], v[102:105], 0
	s_waitcnt vmcnt(14)
	v_mfma_f32_16x16x32_bf16 v[86:89], v[222:225], v[102:105], 0
	s_waitcnt vmcnt(13)
	v_mfma_f32_16x16x32_bf16 v[70:73], v[226:229], v[82:85], v[66:69]
	s_waitcnt vmcnt(12)
	v_mfma_f32_16x16x32_bf16 v[66:69], v[230:233], v[82:85], v[86:89]
	s_waitcnt vmcnt(11)
	v_mfma_f32_16x16x32_bf16 v[86:89], v[234:237], v[102:105], 0
	s_waitcnt vmcnt(10)
	v_mfma_f32_16x16x32_bf16 v[90:93], v[238:241], v[102:105], 0
	s_waitcnt vmcnt(9)
	v_mfma_f32_16x16x32_bf16 v[74:77], v[74:77], v[82:85], v[86:89]
	s_waitcnt vmcnt(8)
	v_mfma_f32_16x16x32_bf16 v[78:81], v[78:81], v[82:85], v[90:93]
	s_nop 1
	ds_read_b128 v[86:89], v218
	ds_read_b128 v[222:225], v218 offset:13888
	ds_read_b128 v[90:93], v218 offset:64
	s_waitcnt lgkmcnt(2)
	v_mfma_f32_16x16x32_bf16 v[86:89], v[86:89], v[102:105], 0
	s_waitcnt lgkmcnt(0)
	v_mfma_f32_16x16x32_bf16 v[114:117], v[90:93], v[82:85], v[86:89]
	ds_read_b128 v[90:93], v218 offset:2368
	s_nop 4
	ds_read_b128 v[86:89], v218 offset:2304
	s_waitcnt lgkmcnt(0)
	v_mfma_f32_16x16x32_bf16 v[86:89], v[86:89], v[102:105], 0
	v_mfma_f32_16x16x32_bf16 v[110:113], v[90:93], v[82:85], v[86:89]
	ds_read_b128 v[90:93], v218 offset:4672
	s_nop 5
	ds_read_b128 v[86:89], v218 offset:4608
	s_waitcnt lgkmcnt(0)
	v_mfma_f32_16x16x32_bf16 v[86:89], v[86:89], v[102:105], 0
	v_mfma_f32_16x16x32_bf16 v[106:109], v[90:93], v[82:85], v[86:89]
	ds_read_b128 v[90:93], v218 offset:6976
	s_nop 5
	ds_read_b128 v[86:89], v218 offset:6912
	s_waitcnt lgkmcnt(0)
	v_mfma_f32_16x16x32_bf16 v[86:89], v[86:89], v[102:105], 0
	v_mfma_f32_16x16x32_bf16 v[98:101], v[90:93], v[82:85], v[86:89]
	ds_read_b128 v[90:93], v218 offset:9280
	s_nop 5
	ds_read_b128 v[86:89], v218 offset:9216
	s_waitcnt lgkmcnt(0)
	v_mfma_f32_16x16x32_bf16 v[86:89], v[86:89], v[102:105], 0
	v_mfma_f32_16x16x32_bf16 v[94:97], v[90:93], v[82:85], v[86:89]
	ds_read_b128 v[90:93], v218 offset:11584
	s_nop 5
	ds_read_b128 v[86:89], v218 offset:11520
	s_waitcnt lgkmcnt(0)
	v_mfma_f32_16x16x32_bf16 v[86:89], v[86:89], v[102:105], 0
	v_mfma_f32_16x16x32_bf16 v[90:93], v[90:93], v[82:85], v[86:89]
	s_nop 6
	ds_read_b128 v[86:89], v218 offset:13824
	s_waitcnt lgkmcnt(0)
	v_mfma_f32_16x16x32_bf16 v[86:89], v[86:89], v[102:105], 0
	v_mfma_f32_16x16x32_bf16 v[86:89], v[222:225], v[82:85], v[86:89]
	ds_read_b128 v[222:225], v218 offset:16128
	s_waitcnt lgkmcnt(0)
	v_mfma_f32_16x16x32_bf16 v[102:105], v[222:225], v[102:105], 0
	ds_read_b128 v[222:225], v218 offset:16192
	s_waitcnt lgkmcnt(0)
	v_mfma_f32_16x16x32_bf16 v[82:85], v[222:225], v[82:85], v[102:105]
	s_nop 4
	v_sub_u32_e32 v102, 0, v217
	v_max_i32_e32 v102, v217, v102
	v_cvt_f32_u32_e32 v102, v102
	v_cndmask_b32_e32 v103, v220, v219, vcc
	v_cmp_gt_i32_e32 vcc, 0, v216
	v_mul_f32_e32 v102, v103, v102
	v_sub_u32_e32 v103, 0, v216
	v_max_i32_e32 v103, v216, v103
	v_cvt_f32_u32_e32 v103, v103
	v_cndmask_b32_e32 v104, v220, v219, vcc
	v_cmp_gt_i32_e32 vcc, 0, v215
	v_exp_f32_e32 v102, v102
	v_mul_f32_e32 v103, v104, v103
	v_sub_u32_e32 v104, 0, v215
	v_max_i32_e32 v104, v215, v104
	v_cvt_f32_u32_e32 v104, v104
	v_cndmask_b32_e32 v105, v220, v219, vcc
	v_cndmask_b32_e64 v102, 2.0, v102, s[82:83]
	v_cmp_gt_i32_e32 vcc, 0, v213
	v_mul_f32_e32 v104, v105, v104
	v_sub_u32_e32 v105, 0, v213
	v_max_i32_e32 v105, v213, v105
	v_cvt_f32_u32_e32 v105, v105
	v_mul_f32_e32 v102, v102, v114
	v_cndmask_b32_e32 v114, v220, v219, vcc
	v_exp_f32_e32 v103, v103
	v_mul_f32_e32 v105, v114, v105
	v_sub_u32_e32 v114, 0, v211
	v_max_i32_e32 v114, v211, v114
	v_cvt_f32_u32_e32 v114, v114
	v_cndmask_b32_e64 v103, 2.0, v103, s[2:3]
	v_cmp_gt_i32_e32 vcc, 0, v211
	v_mul_f32_e32 v103, v103, v115
	v_readlane_b32 s2, v255, 28
	v_cndmask_b32_e32 v115, v220, v219, vcc
	v_mul_f32_e32 v114, v115, v114
	v_exp_f32_e32 v114, v114
	v_cmp_gt_i32_e32 vcc, 0, v209
	v_readlane_b32 s3, v255, 29
	v_exp_f32_e32 v104, v104
	v_cndmask_b32_e64 v114, 2.0, v114, s[74:75]
	v_mul_f32_e32 v110, v114, v110
	v_sub_u32_e32 v114, 0, v209
	v_max_i32_e32 v114, v209, v114
	v_cvt_f32_u32_e32 v114, v114
	v_cndmask_b32_e32 v115, v220, v219, vcc
	v_cmp_gt_i32_e32 vcc, 0, v207
	v_exp_f32_e32 v105, v105
	v_mul_f32_e32 v114, v115, v114
	v_exp_f32_e32 v114, v114
	v_cndmask_b32_e32 v115, v220, v219, vcc
	v_cmp_gt_i32_e32 vcc, 0, v205
	v_cndmask_b32_e64 v104, 2.0, v104, s[78:79]
	v_cndmask_b32_e64 v114, 2.0, v114, s[40:41]
	v_mul_f32_e32 v111, v114, v111
	v_sub_u32_e32 v114, 0, v207
	v_max_i32_e32 v114, v207, v114
	v_cvt_f32_u32_e32 v114, v114
	v_cndmask_b32_e64 v105, 2.0, v105, s[76:77]
	v_mul_f32_e32 v104, v104, v116
	v_mul_f32_e32 v105, v105, v117
	v_mul_f32_e32 v114, v115, v114
	v_exp_f32_e32 v114, v114
	v_cndmask_b32_e32 v115, v220, v219, vcc
	v_cmp_gt_i32_e32 vcc, 0, v203
	v_cndmask_b32_e64 v114, 2.0, v114, s[94:95]
	v_mul_f32_e32 v112, v114, v112
	v_sub_u32_e32 v114, 0, v205
	v_max_i32_e32 v114, v205, v114
	v_cvt_f32_u32_e32 v114, v114
	v_mul_f32_e32 v114, v115, v114
	v_exp_f32_e32 v114, v114
	v_cndmask_b32_e32 v115, v220, v219, vcc
	v_cmp_gt_i32_e32 vcc, 0, v201
	v_cndmask_b32_e64 v114, 2.0, v114, s[52:53]
	v_mul_f32_e32 v113, v114, v113
	v_sub_u32_e32 v114, 0, v203
	v_max_i32_e32 v114, v203, v114
	v_cvt_f32_u32_e32 v114, v114
	v_mul_f32_e32 v114, v115, v114
	v_exp_f32_e32 v114, v114
	v_cndmask_b32_e32 v115, v220, v219, vcc
	v_cmp_gt_i32_e32 vcc, 0, v199
	v_cndmask_b32_e64 v114, 2.0, v114, s[50:51]
	v_mul_f32_e32 v106, v114, v106
	v_sub_u32_e32 v114, 0, v201
	v_max_i32_e32 v114, v201, v114
	v_cvt_f32_u32_e32 v114, v114
	v_mul_f32_e32 v114, v115, v114
	v_exp_f32_e32 v114, v114
	v_cndmask_b32_e32 v115, v220, v219, vcc
	v_cmp_gt_i32_e32 vcc, 0, v197
	v_cndmask_b32_e64 v114, 2.0, v114, s[48:49]
	v_mul_f32_e32 v107, v114, v107
	v_sub_u32_e32 v114, 0, v199
	v_max_i32_e32 v114, v199, v114
	v_cvt_f32_u32_e32 v114, v114
	v_mul_f32_e32 v114, v115, v114
	v_exp_f32_e32 v114, v114
	v_cndmask_b32_e32 v115, v220, v219, vcc
	v_cmp_gt_i32_e32 vcc, 0, v195
	v_cndmask_b32_e64 v114, 2.0, v114, s[46:47]
	v_mul_f32_e32 v108, v114, v108
	v_sub_u32_e32 v114, 0, v197
	v_max_i32_e32 v114, v197, v114
	v_cvt_f32_u32_e32 v114, v114
	v_mul_f32_e32 v114, v115, v114
	v_exp_f32_e32 v114, v114
	v_cndmask_b32_e32 v115, v220, v219, vcc
	v_cmp_gt_i32_e32 vcc, 0, v193
	v_cndmask_b32_e64 v114, 2.0, v114, s[2:3]
	v_mul_f32_e32 v109, v114, v109
	v_sub_u32_e32 v114, 0, v195
	v_max_i32_e32 v114, v195, v114
	v_cvt_f32_u32_e32 v114, v114
	v_readlane_b32 s2, v255, 32
	v_readlane_b32 s3, v255, 33
	v_mul_f32_e32 v114, v115, v114
	v_exp_f32_e32 v114, v114
	v_cndmask_b32_e32 v115, v220, v219, vcc
	v_cmp_gt_i32_e32 vcc, 0, v174
	v_cndmask_b32_e64 v114, 2.0, v114, s[2:3]
	v_mul_f32_e32 v98, v114, v98
	v_sub_u32_e32 v114, 0, v193
	v_max_i32_e32 v114, v193, v114
	v_cvt_f32_u32_e32 v114, v114
	v_readlane_b32 s2, v255, 30
	v_readlane_b32 s3, v255, 31
	v_mul_f32_e32 v114, v115, v114
	v_exp_f32_e32 v114, v114
	v_cndmask_b32_e32 v115, v220, v219, vcc
	v_cmp_gt_i32_e32 vcc, 0, v172
	v_cndmask_b32_e64 v114, 2.0, v114, s[2:3]
	v_mul_f32_e32 v99, v114, v99
	v_sub_u32_e32 v114, 0, v174
	v_max_i32_e32 v114, v174, v114
	v_cvt_f32_u32_e32 v114, v114
	v_readlane_b32 s2, v255, 36
	v_readlane_b32 s3, v255, 37
	v_mul_f32_e32 v114, v115, v114
	v_exp_f32_e32 v114, v114
	v_cndmask_b32_e32 v115, v220, v219, vcc
	v_cmp_gt_i32_e32 vcc, 0, v170
	v_cndmask_b32_e64 v114, 2.0, v114, s[2:3]
	v_mul_f32_e32 v100, v114, v100
	v_sub_u32_e32 v114, 0, v172
	v_max_i32_e32 v114, v172, v114
	v_cvt_f32_u32_e32 v114, v114
	v_readlane_b32 s2, v255, 34
	v_readlane_b32 s3, v255, 35
	v_mul_f32_e32 v114, v115, v114
	v_exp_f32_e32 v114, v114
	v_cndmask_b32_e32 v115, v220, v219, vcc
	v_cmp_gt_i32_e32 vcc, 0, v168
	v_cndmask_b32_e64 v114, 2.0, v114, s[2:3]
	v_mul_f32_e32 v101, v114, v101
	v_sub_u32_e32 v114, 0, v170
	v_max_i32_e32 v114, v170, v114
	v_cvt_f32_u32_e32 v114, v114
	v_readlane_b32 s2, v255, 24
	v_readlane_b32 s3, v255, 25
	v_mul_f32_e32 v114, v115, v114
	v_exp_f32_e32 v114, v114
	v_cndmask_b32_e32 v115, v220, v219, vcc
	v_cmp_gt_i32_e32 vcc, 0, v166
	v_cndmask_b32_e64 v114, 2.0, v114, s[2:3]
	v_mul_f32_e32 v94, v114, v94
	v_sub_u32_e32 v114, 0, v168
	v_max_i32_e32 v114, v168, v114
	v_cvt_f32_u32_e32 v114, v114
	v_readlane_b32 s2, v255, 22
	v_readlane_b32 s3, v255, 23
	v_mul_f32_e32 v114, v115, v114
	v_exp_f32_e32 v114, v114
	v_cndmask_b32_e32 v115, v220, v219, vcc
	v_cmp_gt_i32_e32 vcc, 0, v165
	v_cndmask_b32_e64 v114, 2.0, v114, s[2:3]
	v_mul_f32_e32 v95, v114, v95
	v_sub_u32_e32 v114, 0, v166
	v_max_i32_e32 v114, v166, v114
	v_cvt_f32_u32_e32 v114, v114
	v_readlane_b32 s2, v255, 48
	v_readlane_b32 s3, v255, 49
	v_mul_f32_e32 v114, v115, v114
	v_exp_f32_e32 v114, v114
	v_cndmask_b32_e32 v115, v220, v219, vcc
	v_cmp_gt_i32_e32 vcc, 0, v151
	v_cndmask_b32_e64 v114, 2.0, v114, s[2:3]
	v_mul_f32_e32 v96, v114, v96
	v_sub_u32_e32 v114, 0, v165
	v_max_i32_e32 v114, v165, v114
	v_cvt_f32_u32_e32 v114, v114
	v_readlane_b32 s2, v255, 46
	v_readlane_b32 s3, v255, 47
	v_mul_f32_e32 v114, v115, v114
	v_exp_f32_e32 v114, v114
	v_cndmask_b32_e32 v115, v220, v219, vcc
	v_cmp_gt_i32_e32 vcc, 0, v150
	v_cndmask_b32_e64 v114, 2.0, v114, s[2:3]
	v_mul_f32_e32 v97, v114, v97
	v_sub_u32_e32 v114, 0, v151
	v_max_i32_e32 v114, v151, v114
	v_cvt_f32_u32_e32 v114, v114
	v_readlane_b32 s2, v255, 52
	v_readlane_b32 s3, v255, 53
	v_mul_f32_e32 v114, v115, v114
	v_exp_f32_e32 v114, v114
	v_cndmask_b32_e32 v115, v220, v219, vcc
	v_cndmask_b32_e64 v114, 2.0, v114, s[2:3]
	v_mul_f32_e32 v90, v114, v90
	v_sub_u32_e32 v114, 0, v150
	v_max_i32_e32 v114, v150, v114
	v_cvt_f32_u32_e32 v114, v114
	v_readlane_b32 s2, v255, 40
	v_readlane_b32 s3, v255, 41
	v_mul_f32_e32 v114, v115, v114
	v_exp_f32_e32 v114, v114
	s_nop 0
	v_cndmask_b32_e64 v114, 2.0, v114, s[2:3]
	v_mul_f32_e32 v91, v114, v91
	v_sub_u32_e32 v114, v134, v147
	v_sub_u32_e32 v115, 0, v114
	v_cmp_gt_i32_e32 vcc, 0, v114
	v_max_i32_e32 v114, v114, v115
	v_cvt_f32_u32_e32 v114, v114
	v_cndmask_b32_e32 v115, v220, v219, vcc
	v_cmp_ne_u32_e32 vcc, v134, v147
	v_mul_f32_e32 v114, v115, v114
	v_exp_f32_e32 v114, v114
	s_nop 0
	v_cndmask_b32_e32 v114, 2.0, v114, vcc
	v_mul_f32_e32 v92, v114, v92
	v_sub_u32_e32 v114, v134, v145
	v_sub_u32_e32 v115, 0, v114
	v_cmp_gt_i32_e32 vcc, 0, v114
	v_max_i32_e32 v114, v114, v115
	v_cvt_f32_u32_e32 v114, v114
	v_cndmask_b32_e32 v115, v220, v219, vcc
	v_cmp_ne_u32_e32 vcc, v134, v145
	v_mul_f32_e32 v114, v115, v114
	v_exp_f32_e32 v114, v114
	s_nop 0
	v_cndmask_b32_e32 v114, 2.0, v114, vcc
	v_mul_f32_e32 v93, v114, v93
	v_sub_u32_e32 v114, v134, v144
	v_sub_u32_e32 v115, 0, v114
	v_cmp_gt_i32_e32 vcc, 0, v114
	v_max_i32_e32 v114, v114, v115
	v_cvt_f32_u32_e32 v114, v114
	v_cndmask_b32_e32 v115, v220, v219, vcc
	v_cmp_ne_u32_e32 vcc, v134, v144
	v_mul_f32_e32 v114, v115, v114
	v_exp_f32_e32 v114, v114
	s_nop 0
	v_cndmask_b32_e32 v114, 2.0, v114, vcc
	v_mul_f32_e32 v86, v114, v86
	v_sub_u32_e32 v114, v134, v143
	v_sub_u32_e32 v115, 0, v114
	v_cmp_gt_i32_e32 vcc, 0, v114
	v_max_i32_e32 v114, v114, v115
	v_cvt_f32_u32_e32 v114, v114
	v_cndmask_b32_e32 v115, v220, v219, vcc
	v_cmp_ne_u32_e32 vcc, v134, v143
	v_mul_f32_e32 v114, v115, v114
	v_exp_f32_e32 v114, v114
	s_nop 0
	v_cndmask_b32_e32 v114, 2.0, v114, vcc
	v_mul_f32_e32 v87, v114, v87
	v_sub_u32_e32 v114, v134, v142
	v_sub_u32_e32 v115, 0, v114
	v_cmp_gt_i32_e32 vcc, 0, v114
	v_max_i32_e32 v114, v114, v115
	v_cvt_f32_u32_e32 v114, v114
	v_cndmask_b32_e32 v115, v220, v219, vcc
	v_cmp_ne_u32_e32 vcc, v134, v142
	v_mul_f32_e32 v114, v115, v114
	v_exp_f32_e32 v114, v114
	s_nop 0
	v_cndmask_b32_e32 v114, 2.0, v114, vcc
	v_mul_f32_e32 v88, v114, v88
	v_sub_u32_e32 v114, v134, v133
	v_sub_u32_e32 v115, 0, v114
	v_cmp_gt_i32_e32 vcc, 0, v114
	v_max_i32_e32 v114, v114, v115
	v_cvt_f32_u32_e32 v114, v114
	v_cndmask_b32_e32 v115, v220, v219, vcc
	v_cmp_ne_u32_e32 vcc, v134, v133
	v_mul_f32_e32 v114, v115, v114
	v_exp_f32_e32 v114, v114
	s_nop 0
	v_cndmask_b32_e32 v114, 2.0, v114, vcc
	v_mul_f32_e32 v89, v114, v89
	v_sub_u32_e32 v114, v134, v132
	v_sub_u32_e32 v115, 0, v114
	v_cmp_gt_i32_e32 vcc, 0, v114
	v_max_i32_e32 v114, v114, v115
	v_cvt_f32_u32_e32 v114, v114
	v_cndmask_b32_e32 v115, v220, v219, vcc
	v_cmp_ne_u32_e32 vcc, v134, v132
	v_mul_f32_e32 v114, v115, v114
	v_exp_f32_e32 v114, v114
	s_nop 0
	v_cndmask_b32_e32 v114, 2.0, v114, vcc
	v_mul_f32_e32 v137, v114, v82
	v_sub_u32_e32 v82, v134, v131
	v_sub_u32_e32 v114, 0, v82
	v_cmp_gt_i32_e32 vcc, 0, v82
	v_max_i32_e32 v82, v82, v114
	v_cvt_f32_u32_e32 v82, v82
	v_cndmask_b32_e32 v114, v220, v219, vcc
	v_cmp_ne_u32_e32 vcc, v134, v131
	v_mul_f32_e32 v82, v114, v82
	v_exp_f32_e32 v82, v82
	s_nop 0
	v_cndmask_b32_e32 v82, 2.0, v82, vcc
	v_mul_f32_e32 v182, v82, v83
	v_sub_u32_e32 v82, v134, v130
	v_sub_u32_e32 v83, 0, v82
	v_cmp_gt_i32_e32 vcc, 0, v82
	v_max_i32_e32 v82, v82, v83
	v_cvt_f32_u32_e32 v82, v82
	v_cndmask_b32_e32 v83, v220, v219, vcc
	v_cmp_ne_u32_e32 vcc, v134, v130
	v_mul_f32_e32 v82, v83, v82
	v_exp_f32_e32 v82, v82
	s_nop 0
	v_cndmask_b32_e32 v82, 2.0, v82, vcc
	v_mul_f32_e32 v183, v82, v84
	v_sub_u32_e32 v82, v134, v129
	v_sub_u32_e32 v83, 0, v82
	v_cmp_gt_i32_e32 vcc, 0, v82
	v_max_i32_e32 v82, v82, v83
	v_cvt_f32_u32_e32 v82, v82
	v_cndmask_b32_e32 v83, v220, v219, vcc
	v_cmp_ne_u32_e32 vcc, v134, v129
	v_mul_f32_e32 v82, v83, v82
	v_exp_f32_e32 v82, v82
	s_nop 0
	v_cndmask_b32_e32 v82, 2.0, v82, vcc
	v_mul_f32_e32 v184, v82, v85
	v_cvt_pk_bf16_f32 v82, v102, v103
	v_cvt_pk_bf16_f32 v83, v104, v105
	v_cvt_pk_bf16_f32 v84, v110, v111
	v_cvt_pk_bf16_f32 v85, v112, v113
	ds_read_b64_tr_b16 v[104:105], v128 offset:20736
	ds_read_b64_tr_b16 v[102:103], v128 offset:18432
	ds_read_b64_tr_b16 v[110:111], v128 offset:18464
	ds_read_b64_tr_b16 v[112:113], v128 offset:20768
	ds_read_b64_tr_b16 v[114:115], v128 offset:18496
	ds_read_b64_tr_b16 v[116:117], v128 offset:20800
	ds_read_b64_tr_b16 v[222:223], v128 offset:18528
	ds_read_b64_tr_b16 v[224:225], v128 offset:20832
	s_waitcnt lgkmcnt(6)
	v_mfma_f32_16x16x32_bf16 v[102:105], v[102:105], v[82:85], 0
	v_cvt_pk_bf16_f32 v106, v106, v107
	v_cvt_pk_bf16_f32 v107, v108, v109
	v_cvt_pk_bf16_f32 v108, v98, v99
	s_waitcnt lgkmcnt(4)
	v_mfma_f32_16x16x32_bf16 v[110:113], v[110:113], v[82:85], 0
	v_cvt_pk_bf16_f32 v109, v100, v101
	s_waitcnt lgkmcnt(2)
	v_mfma_f32_16x16x32_bf16 v[114:117], v[114:117], v[82:85], 0
	s_waitcnt lgkmcnt(0)
	v_mfma_f32_16x16x32_bf16 v[82:85], v[222:225], v[82:85], 0
	ds_read_b64_tr_b16 v[100:101], v128 offset:25344
	ds_read_b64_tr_b16 v[98:99], v128 offset:23040
	ds_read_b64_tr_b16 v[222:223], v128 offset:23072
	ds_read_b64_tr_b16 v[224:225], v128 offset:25376
	s_waitcnt lgkmcnt(2)
	v_mfma_f32_16x16x32_bf16 v[98:101], v[98:101], v[106:109], v[102:105]
	s_waitcnt lgkmcnt(0)
	v_mfma_f32_16x16x32_bf16 v[102:105], v[222:225], v[106:109], v[110:113]
	s_nop 2
	ds_read_b64_tr_b16 v[110:111], v128 offset:23104
	ds_read_b64_tr_b16 v[112:113], v128 offset:25408
	s_waitcnt lgkmcnt(0)
	v_mfma_f32_16x16x32_bf16 v[110:113], v[110:113], v[106:109], v[114:117]
	s_nop 2
	ds_read_b64_tr_b16 v[114:115], v128 offset:23136
	ds_read_b64_tr_b16 v[116:117], v128 offset:25440
	v_cvt_pk_bf16_f32 v94, v94, v95
	v_cvt_pk_bf16_f32 v95, v96, v97
	s_waitcnt lgkmcnt(0)
	v_mfma_f32_16x16x32_bf16 v[82:85], v[114:117], v[106:109], v[82:85]
	v_cvt_pk_bf16_f32 v96, v90, v91
	v_cvt_pk_bf16_f32 v97, v92, v93
	ds_read_b64_tr_b16 v[92:93], v128 offset:29952
	ds_read_b64_tr_b16 v[90:91], v128 offset:27648
	ds_read_b64_tr_b16 v[106:107], v128 offset:27680
	ds_read_b64_tr_b16 v[108:109], v128 offset:29984
	s_waitcnt lgkmcnt(2)
	v_mfma_f32_16x16x32_bf16 v[90:93], v[90:93], v[94:97], v[98:101]
	s_waitcnt lgkmcnt(0)
	v_mfma_f32_16x16x32_bf16 v[98:101], v[106:109], v[94:97], v[102:105]
	s_nop 2
	ds_read_b64_tr_b16 v[102:103], v128 offset:27712
	ds_read_b64_tr_b16 v[104:105], v128 offset:30016
	ds_read_b64_tr_b16 v[106:107], v128 offset:27744
	ds_read_b64_tr_b16 v[108:109], v128 offset:30048
	v_cvt_pk_bf16_f32 v86, v86, v87
	s_waitcnt lgkmcnt(2)
	v_mfma_f32_16x16x32_bf16 v[102:105], v[102:105], v[94:97], v[110:113]
	v_cvt_pk_bf16_f32 v87, v88, v89
	v_cvt_pk_bf16_f32 v88, v137, v182
	v_cvt_pk_bf16_f32 v89, v183, v184
	s_waitcnt lgkmcnt(0)
	v_mfma_f32_16x16x32_bf16 v[82:85], v[106:109], v[94:97], v[82:85]
	ds_read_b64_tr_b16 v[96:97], v128 offset:34560
	ds_read_b64_tr_b16 v[94:95], v128 offset:32256
	ds_read_b64_tr_b16 v[106:107], v128 offset:32288
	ds_read_b64_tr_b16 v[108:109], v128 offset:34592
	s_waitcnt lgkmcnt(2)
	v_mfma_f32_16x16x32_bf16 v[90:93], v[94:97], v[86:89], v[90:93]
	s_waitcnt lgkmcnt(0)
	v_mfma_f32_16x16x32_bf16 v[94:97], v[106:109], v[86:89], v[98:101]
	s_nop 2
	ds_read_b64_tr_b16 v[98:99], v128 offset:32320
	ds_read_b64_tr_b16 v[100:101], v128 offset:34624
	s_waitcnt lgkmcnt(0)
	v_mfma_f32_16x16x32_bf16 v[98:101], v[98:101], v[86:89], v[102:105]
	s_nop 2
	ds_read_b64_tr_b16 v[102:103], v128 offset:32352
	ds_read_b64_tr_b16 v[104:105], v128 offset:34656
	s_waitcnt lgkmcnt(0)
	v_mfma_f32_16x16x32_bf16 v[82:85], v[102:105], v[86:89], v[82:85]
	v_mul_f32_e32 v86, v220, v139
	v_exp_f32_e32 v86, v86
	v_mul_f32_e32 v87, v219, v141
	v_exp_f32_e32 v88, v87
	v_pk_fma_f32 v[40:41], v[86:87], v[40:41], v[92:93] op_sel_hi:[0,1,1]
	v_pk_fma_f32 v[38:39], v[86:87], v[38:39], v[90:91] op_sel_hi:[0,1,1]
	v_pk_fma_f32 v[36:37], v[88:89], v[36:37], v[40:41] op_sel_hi:[0,1,1]
	v_pk_fma_f32 v[34:35], v[88:89], v[34:35], v[38:39] op_sel_hi:[0,1,1]
	v_add_f32_e32 v38, v34, v35
	v_add_f32_e32 v39, v36, v37
	v_add_f32_e32 v38, v38, v39
	v_add_f32_e32 v87, 0, v38
	v_pk_fma_f32 v[38:39], v[86:87], v[48:49], v[96:97] op_sel_hi:[0,1,1]
	v_pk_fma_f32 v[40:41], v[86:87], v[46:47], v[94:95] op_sel_hi:[0,1,1]
	v_pk_fma_f32 v[38:39], v[88:89], v[44:45], v[38:39] op_sel_hi:[0,1,1]
	v_pk_fma_f32 v[40:41], v[88:89], v[42:43], v[40:41] op_sel_hi:[0,1,1]
	v_add_f32_e32 v42, v40, v41
	v_add_f32_e32 v43, v38, v39
	v_add_f32_e32 v42, v42, v43
	v_add_f32_e32 v46, v87, v42
	v_pk_fma_f32 v[42:43], v[86:87], v[72:73], v[100:101] op_sel_hi:[0,1,1]
	v_pk_fma_f32 v[44:45], v[86:87], v[70:71], v[98:99] op_sel_hi:[0,1,1]
	v_pk_fma_f32 v[42:43], v[88:89], v[68:69], v[42:43] op_sel_hi:[0,1,1]
	v_pk_fma_f32 v[44:45], v[88:89], v[66:67], v[44:45] op_sel_hi:[0,1,1]
	v_add_f32_e32 v47, v44, v45
	v_add_f32_e32 v48, v42, v43
	v_add_f32_e32 v47, v47, v48
	v_add_f32_e32 v66, v46, v47
	v_pk_fma_f32 v[46:47], v[86:87], v[76:77], v[84:85] op_sel_hi:[0,1,1]
	v_pk_fma_f32 v[48:49], v[86:87], v[74:75], v[82:83] op_sel_hi:[0,1,1]
	v_pk_fma_f32 v[46:47], v[88:89], v[80:81], v[46:47] op_sel_hi:[0,1,1]
	v_pk_fma_f32 v[48:49], v[88:89], v[78:79], v[48:49] op_sel_hi:[0,1,1]
	v_add_f32_e32 v67, v48, v49
	v_add_f32_e32 v68, v46, v47
	v_add_f32_e32 v67, v67, v68
	v_add_f32_e32 v66, v66, v67
	v_mov_b32_e32 v67, v66
	s_nop 1
	v_permlane16_swap_b32_e32 v66, v67
	v_add_f32_e32 v66, v66, v67
	v_mov_b32_e32 v67, v66
	s_nop 1
	v_permlane32_swap_b32_e32 v66, v67
	v_add_f32_e32 v66, v66, v67
	v_fmac_f32_e32 v37, 0xbc800000, v66
	v_fmac_f32_e32 v35, 0xbc800000, v66
	v_fmamk_f32 v36, v66, 0xbc800000, v36
	v_fmamk_f32 v34, v66, 0xbc800000, v34
	v_mul_f32_e32 v67, v35, v35
	v_mul_f32_e32 v68, v37, v37
	v_fmac_f32_e32 v67, v34, v34
	v_fmac_f32_e32 v68, v36, v36
	v_fmac_f32_e32 v39, 0xbc800000, v66
	v_fmac_f32_e32 v41, 0xbc800000, v66
	v_add_f32_e32 v67, v67, v68
	v_fmamk_f32 v38, v66, 0xbc800000, v38
	v_fmamk_f32 v40, v66, 0xbc800000, v40
	v_mul_f32_e32 v68, v41, v41
	v_mul_f32_e32 v69, v39, v39
	v_fmac_f32_e32 v68, v40, v40
	v_fmac_f32_e32 v69, v38, v38
	v_add_f32_e32 v68, v68, v69
	v_fmac_f32_e32 v43, 0xbc800000, v66
	v_fmac_f32_e32 v45, 0xbc800000, v66
	v_add_f32_e32 v67, v67, v68
	v_fmamk_f32 v42, v66, 0xbc800000, v42
	v_fmamk_f32 v44, v66, 0xbc800000, v44
	v_mul_f32_e32 v68, v45, v45
	v_mul_f32_e32 v69, v43, v43
	v_fmac_f32_e32 v68, v44, v44
	v_fmac_f32_e32 v69, v42, v42
	v_add_f32_e32 v68, v68, v69
	v_fmac_f32_e32 v47, 0xbc800000, v66
	v_fmac_f32_e32 v49, 0xbc800000, v66
	v_add_f32_e32 v67, v68, v67
	v_fmamk_f32 v46, v66, 0xbc800000, v46
	v_fmamk_f32 v48, v66, 0xbc800000, v48
	v_mul_f32_e32 v66, v49, v49
	v_mul_f32_e32 v68, v47, v47
	v_fmac_f32_e32 v66, v48, v48
	v_fmac_f32_e32 v68, v46, v46
	v_add_f32_e32 v66, v66, v68
	v_add_f32_e32 v66, v66, v67
	v_mov_b32_e32 v67, v66
	s_nop 1
	v_permlane16_swap_b32_e32 v66, v67
	v_add_f32_e32 v66, v66, v67
	v_mov_b32_e32 v67, v66
	s_nop 1
	v_permlane32_swap_b32_e32 v66, v67
	v_add_f32_e32 v66, v66, v67
	v_fmamk_f32 v66, v66, 0x3c800000, v177
	v_rsq_f32_e32 v66, v66
	v_lshlrev_b64 v[68:69], 11, v[118:119]
	s_waitcnt vmcnt(7)
	v_lshlrev_b32_e32 v70, 16, v126
	v_and_b32_e32 v71, 0xffff0000, v126
	v_pk_mul_f32 v[36:37], v[36:37], v[66:67] op_sel_hi:[1,0]
	v_pk_mul_f32 v[34:35], v[34:35], v[66:67] op_sel_hi:[1,0]
	v_lshlrev_b32_e32 v72, 16, v127
	v_and_b32_e32 v73, 0xffff0000, v127
	s_waitcnt vmcnt(6)
	v_pk_mul_f32 v[34:35], v[62:63], v[34:35]
	v_pk_mul_f32 v[36:37], v[64:65], v[36:37]
	v_lshl_add_u64 v[68:69], s[70:71], 0, v[68:69]
	v_pk_mul_f32 v[36:37], v[36:37], v[72:73]
	v_pk_mul_f32 v[34:35], v[34:35], v[70:71]
	v_pk_mul_f32 v[40:41], v[40:41], v[66:67] op_sel_hi:[1,0]
	v_cvt_pk_bf16_f32 v34, v34, v35
	v_cvt_pk_bf16_f32 v35, v36, v37
	v_lshl_add_u64 v[36:37], v[68:69], 0, v[0:1]
	global_store_dwordx2 v[36:37], v[34:35], off
	s_waitcnt vmcnt(6)
	v_lshlrev_b32_e32 v34, 16, v124
	v_and_b32_e32 v35, 0xffff0000, v124
	v_pk_mul_f32 v[38:39], v[38:39], v[66:67] op_sel_hi:[1,0]
	s_waitcnt vmcnt(5)
	v_pk_mul_f32 v[40:41], v[58:59], v[40:41]
	v_lshlrev_b32_e32 v62, 16, v125
	v_and_b32_e32 v63, 0xffff0000, v125
	v_pk_mul_f32 v[38:39], v[60:61], v[38:39]
	v_pk_mul_f32 v[34:35], v[40:41], v[34:35]
	v_pk_mul_f32 v[38:39], v[38:39], v[62:63]
	v_cvt_pk_bf16_f32 v34, v34, v35
	v_pk_mul_f32 v[40:41], v[42:43], v[66:67] op_sel_hi:[1,0]
	v_cvt_pk_bf16_f32 v35, v38, v39
	v_pk_mul_f32 v[42:43], v[44:45], v[66:67] op_sel_hi:[1,0]
	global_store_dwordx2 v[36:37], v[34:35], off offset:32
	s_waitcnt vmcnt(5)
	v_lshlrev_b32_e32 v34, 16, v122
	v_and_b32_e32 v35, 0xffff0000, v122
	s_waitcnt vmcnt(4)
	v_pk_mul_f32 v[42:43], v[54:55], v[42:43]
	v_lshlrev_b32_e32 v38, 16, v123
	v_and_b32_e32 v39, 0xffff0000, v123
	v_pk_mul_f32 v[40:41], v[56:57], v[40:41]
	v_pk_mul_f32 v[34:35], v[42:43], v[34:35]
	v_pk_mul_f32 v[38:39], v[40:41], v[38:39]
	v_cvt_pk_bf16_f32 v34, v34, v35
	v_pk_mul_f32 v[42:43], v[48:49], v[66:67] op_sel_hi:[1,0]
	v_cvt_pk_bf16_f32 v35, v38, v39
	global_store_dwordx2 v[36:37], v[34:35], off offset:64
	s_waitcnt vmcnt(4)
	v_lshlrev_b32_e32 v34, 16, v120
	v_and_b32_e32 v35, 0xffff0000, v120
	v_pk_mul_f32 v[40:41], v[46:47], v[66:67] op_sel_hi:[1,0]
	s_waitcnt vmcnt(3)
	v_pk_mul_f32 v[42:43], v[50:51], v[42:43]
	v_lshlrev_b32_e32 v38, 16, v121
	v_and_b32_e32 v39, 0xffff0000, v121
	v_pk_mul_f32 v[40:41], v[52:53], v[40:41]
	v_pk_mul_f32 v[34:35], v[42:43], v[34:35]
	v_pk_mul_f32 v[38:39], v[40:41], v[38:39]
	v_cvt_pk_bf16_f32 v34, v34, v35
	s_nop 0
	v_cvt_pk_bf16_f32 v35, v38, v39
	global_store_dwordx2 v[36:37], v[34:35], off offset:96
	s_barrier
.LBB0_44:
	v_readlane_b32 s2, v253, 31
	v_readlane_b32 s46, v255, 18
	s_cmp_ge_i32 s2, s15
	v_readlane_b32 s47, v255, 19
	s_cbranch_scc1 .LBB0_46
	v_readlane_b32 s2, v253, 26
	v_readlane_b32 s3, v253, 27
	s_waitcnt vmcnt(4)
	v_mov_b64_e32 v[34:35], s[72:73]
	v_readlane_b32 s20, v253, 28
	v_lshl_add_u64 v[98:99], s[2:3], 0, v[134:135]
	v_mad_u64_u32 v[86:87], s[2:3], v98, s64, v[34:35]
	s_lshl_b32 s16, s20, 1
	v_readlane_b32 s2, v253, 29
	v_readlane_b32 s3, v253, 30
	s_add_u32 s2, s42, s2
	v_mad_i32_i24 v87, v99, s64, v87
	s_addc_u32 s3, s43, s3
	v_lshl_add_u64 v[38:39], v[86:87], 0, s[16:17]
	v_mov_b32_e32 v137, v1
	s_add_u32 s10, s2, 0x2000
	v_lshl_add_u64 v[62:63], v[38:39], 0, v[136:137]
	s_addc_u32 s11, s3, 0
	global_load_dwordx4 v[34:37], v159, s[2:3]
	global_load_dwordx4 v[66:69], v[62:63], off
	global_load_dwordx4 v[38:41], v159, s[2:3] offset:2048
	global_load_dwordx4 v[42:45], v158, s[2:3]
	global_load_dwordx4 v[46:49], v156, s[2:3]
	global_load_dwordx4 v[50:53], v159, s[10:11]
	global_load_dwordx4 v[54:57], v161, s[10:11]
	global_load_dwordx4 v[58:61], v158, s[10:11]
	global_load_dwordx4 v[70:73], v156, s[10:11]
	global_load_dwordx4 v[88:91], v159, s[2:3] offset:64
	global_load_dwordx4 v[92:95], v159, s[2:3] offset:2112
	global_load_dwordx4 v[74:77], v[62:63], off offset:64
	global_load_dwordx4 v[100:103], v157, s[2:3]
	global_load_dwordx4 v[78:81], v157, s[10:11]
	global_load_dwordx4 v[110:113], v155, s[2:3]
	global_load_dwordx4 v[114:117], v162, s[10:11]
	global_load_dwordx4 v[82:85], v160, s[10:11]
	v_sub_u32_e32 v126, 0, v217
	v_cmp_gt_i32_e64 s[40:41], 0, v217
	v_cmp_ne_u32_e32 vcc, v134, v152
	s_waitcnt vmcnt(14)
	v_mfma_f32_16x16x32_bf16 v[38:41], v[38:41], v[66:69], 0
	s_waitcnt vmcnt(10)
	v_mfma_f32_16x16x32_bf16 v[62:65], v[54:57], v[66:69], 0
	s_waitcnt vmcnt(9)
	v_mfma_f32_16x16x32_bf16 v[54:57], v[58:61], v[66:69], 0
	s_waitcnt vmcnt(8)
	v_mfma_f32_16x16x32_bf16 v[58:61], v[70:73], v[66:69], 0
	global_load_dwordx4 v[70:73], v155, s[10:11]
	v_readlane_b32 s2, v254, 37
	v_mfma_f32_16x16x32_bf16 v[34:37], v[34:37], v[66:69], 0
	s_nop 0
	v_mov_b32_e32 v0, s2
	global_load_dword v108, v0, s[28:29]
	global_load_dword v109, v0, s[28:29] offset:16
	ds_write_b128 v153, v[22:25]
	ds_write_b128 v153, v[18:21] offset:16
	ds_write_b128 v153, v[30:33] offset:18432
	v_mfma_f32_16x16x32_bf16 v[42:45], v[42:45], v[66:69], 0
	ds_write_b128 v153, v[26:29] offset:18448
	v_mfma_f32_16x16x32_bf16 v[104:107], v[46:49], v[66:69], 0
	v_mfma_f32_16x16x32_bf16 v[50:53], v[50:53], v[66:69], 0
	s_waitcnt vmcnt(8)
	v_mfma_f32_16x16x32_bf16 v[34:37], v[88:91], v[74:77], v[34:37]
	v_or_b32_e32 v88, s20, v152
	v_lshlrev_b32_e32 v0, 1, v88
	v_lshlrev_b32_e32 v18, 2, v88
	v_mfma_f32_16x16x32_bf16 v[46:49], v[92:95], v[74:77], v[38:41]
	v_lshl_add_u64 v[86:87], v[86:87], 0, v[0:1]
	global_load_dwordx4 v[30:33], v18, s[44:45]
	global_load_dwordx4 v[26:29], v18, s[44:45] offset:64
	global_load_dwordx4 v[22:25], v18, s[44:45] offset:128
	s_waitcnt vmcnt(10)
	v_mfma_f32_16x16x32_bf16 v[38:41], v[100:103], v[74:77], v[42:45]
	global_load_dwordx4 v[18:21], v18, s[44:45] offset:192
	s_waitcnt vmcnt(9)
	v_mfma_f32_16x16x32_bf16 v[42:45], v[110:113], v[74:77], v[104:107]
	s_waitcnt vmcnt(8)
	v_mfma_f32_16x16x32_bf16 v[50:53], v[114:117], v[74:77], v[50:53]
	s_nop 0
	global_load_dwordx2 v[104:105], v[86:87], off offset:1536
	global_load_dwordx2 v[106:107], v[86:87], off offset:1568
	global_load_dwordx2 v[102:103], v[86:87], off offset:1600
	global_load_dwordx2 v[100:101], v[86:87], off offset:1632
	s_waitcnt vmcnt(11) lgkmcnt(0)
	v_mfma_f32_16x16x32_bf16 v[62:65], v[82:85], v[74:77], v[62:65]
	s_barrier
	v_mfma_f32_16x16x32_bf16 v[54:57], v[78:81], v[74:77], v[54:57]
	s_waitcnt vmcnt(10)
	v_mfma_f32_16x16x32_bf16 v[58:61], v[70:73], v[74:77], v[58:61]
	ds_read_b128 v[70:73], v218
	ds_read_b128 v[78:81], v218 offset:2304
	ds_read_b128 v[90:93], v218 offset:9216
	ds_read_b128 v[94:97], v218 offset:11520
	ds_read_b128 v[82:85], v218 offset:4608
	ds_read_b128 v[86:89], v218 offset:6912
	s_waitcnt lgkmcnt(5)
	v_mfma_f32_16x16x32_bf16 v[70:73], v[70:73], v[66:69], 0
	s_waitcnt lgkmcnt(3)
	v_mfma_f32_16x16x32_bf16 v[110:113], v[90:93], v[66:69], 0
	ds_read_b128 v[90:93], v218 offset:64
	ds_read_b128 v[114:117], v218 offset:2368
	ds_read_b128 v[122:125], v218 offset:4672
	v_mfma_f32_16x16x32_bf16 v[78:81], v[78:81], v[66:69], 0
	s_waitcnt lgkmcnt(2)
	v_mfma_f32_16x16x32_bf16 v[220:223], v[90:93], v[74:77], v[70:73]
	v_sub_u32_e32 v90, 0, v216
	s_nop 1
	ds_read_b128 v[70:73], v218 offset:6976
	v_mfma_f32_16x16x32_bf16 v[82:85], v[82:85], v[66:69], 0
	v_mfma_f32_16x16x32_bf16 v[118:121], v[94:97], v[66:69], 0
	s_waitcnt lgkmcnt(2)
	v_mfma_f32_16x16x32_bf16 v[94:97], v[114:117], v[74:77], v[78:81]
	v_max_i32_e32 v114, v217, v126
	v_max_i32_e32 v126, v216, v90
	v_mfma_f32_16x16x32_bf16 v[86:89], v[86:89], v[66:69], 0
	ds_read_b128 v[78:81], v218 offset:9280
	s_waitcnt lgkmcnt(2)
	v_mfma_f32_16x16x32_bf16 v[90:93], v[122:125], v[74:77], v[82:85]
	s_nop 2
	v_cvt_f32_u32_e32 v82, v114
	ds_read_b128 v[114:117], v218 offset:11584
	s_waitcnt vmcnt(8)
	v_cndmask_b32_e64 v83, v108, v109, s[40:41]
	s_waitcnt lgkmcnt(2)
	v_mfma_f32_16x16x32_bf16 v[86:89], v[70:73], v[74:77], v[86:89]
	v_mul_f32_e32 v70, v83, v82
	v_exp_f32_e32 v122, v70
	ds_read_b128 v[70:73], v218 offset:13824
	s_waitcnt lgkmcnt(2)
	v_mfma_f32_16x16x32_bf16 v[82:85], v[78:81], v[74:77], v[110:113]
	v_cmp_gt_i32_e64 s[40:41], 0, v215
	s_nop 1
	v_cvt_f32_u32_e32 v111, v126
	v_cndmask_b32_e32 v110, 2.0, v122, vcc
	ds_read_b128 v[122:125], v218 offset:13888
	s_waitcnt lgkmcnt(2)
	v_mfma_f32_16x16x32_bf16 v[78:81], v[114:117], v[74:77], v[118:121]
	ds_read_b128 v[112:115], v218 offset:16128
	s_nop 1
	ds_read_b128 v[116:119], v218 offset:16192
	v_cmp_gt_i32_e32 vcc, 0, v216
	v_mul_f32_e32 v110, v110, v220
	s_waitcnt lgkmcnt(3)
	v_mfma_f32_16x16x32_bf16 v[70:73], v[70:73], v[66:69], 0
	v_cndmask_b32_e32 v120, v108, v109, vcc
	v_mul_f32_e32 v111, v120, v111
	v_sub_u32_e32 v120, 0, v215
	s_waitcnt lgkmcnt(1)
	v_mfma_f32_16x16x32_bf16 v[66:69], v[112:115], v[66:69], 0
	v_max_i32_e32 v112, v215, v120
	v_cvt_f32_u32_e32 v112, v112
	v_exp_f32_e32 v111, v111
	v_mfma_f32_16x16x32_bf16 v[70:73], v[122:125], v[74:77], v[70:73]
	v_cmp_ne_u32_e32 vcc, v134, v214
	s_waitcnt lgkmcnt(0)
	v_mfma_f32_16x16x32_bf16 v[66:69], v[116:119], v[74:77], v[66:69]
	v_cndmask_b32_e64 v74, v108, v109, s[40:41]
	v_mul_f32_e32 v74, v74, v112
	v_exp_f32_e32 v75, v74
	v_sub_u32_e32 v76, 0, v213
	v_max_i32_e32 v76, v213, v76
	v_cvt_f32_u32_e32 v76, v76
	v_cndmask_b32_e32 v74, 2.0, v111, vcc
	v_cmp_ne_u32_e32 vcc, v134, v212
	v_cmp_gt_i32_e64 s[40:41], 0, v211
	v_mul_f32_e32 v74, v74, v221
	v_cndmask_b32_e32 v75, 2.0, v75, vcc
	v_cmp_gt_i32_e32 vcc, 0, v213
	v_cndmask_b32_e64 v111, v108, v109, s[40:41]
	v_cmp_gt_i32_e64 s[40:41], 0, v207
	v_cndmask_b32_e32 v77, v108, v109, vcc
	v_mul_f32_e32 v76, v77, v76
	v_sub_u32_e32 v77, 0, v211
	v_max_i32_e32 v77, v211, v77
	v_cvt_f32_u32_e32 v77, v77
	v_exp_f32_e32 v76, v76
	v_cmp_ne_u32_e32 vcc, v134, v210
	v_cndmask_b32_e64 v112, v108, v109, s[40:41]
	v_mul_f32_e32 v77, v111, v77
	v_exp_f32_e32 v77, v77
	v_sub_u32_e32 v111, 0, v209
	v_max_i32_e32 v111, v209, v111
	v_cvt_f32_u32_e32 v111, v111
	v_cndmask_b32_e32 v76, 2.0, v76, vcc
	v_cmp_ne_u32_e32 vcc, v134, v208
	v_cmp_gt_i32_e64 s[40:41], 0, v203
	v_mul_f32_e32 v75, v75, v222
	v_cndmask_b32_e32 v77, 2.0, v77, vcc
	v_cmp_gt_i32_e32 vcc, 0, v209
	v_mul_f32_e32 v94, v77, v94
	v_mul_f32_e32 v76, v76, v223
	v_cndmask_b32_e32 v77, v108, v109, vcc
	v_mul_f32_e32 v77, v77, v111
	v_sub_u32_e32 v111, 0, v207
	v_max_i32_e32 v111, v207, v111
	v_cvt_f32_u32_e32 v111, v111
	v_exp_f32_e32 v77, v77
	v_cmp_ne_u32_e32 vcc, v134, v206
	v_mul_f32_e32 v111, v112, v111
	v_exp_f32_e32 v111, v111
	v_cndmask_b32_e32 v77, 2.0, v77, vcc
	v_cmp_ne_u32_e32 vcc, v134, v204
	v_mul_f32_e32 v95, v77, v95
	v_cndmask_b32_e64 v112, v108, v109, s[40:41]
	v_cndmask_b32_e32 v77, 2.0, v111, vcc
	v_sub_u32_e32 v111, 0, v205
	v_max_i32_e32 v111, v205, v111
	v_cvt_f32_u32_e32 v111, v111
	v_cmp_gt_i32_e32 vcc, 0, v205
	v_mul_f32_e32 v96, v77, v96
	v_cmp_gt_i32_e64 s[40:41], 0, v199
	v_cndmask_b32_e32 v77, v108, v109, vcc
	v_mul_f32_e32 v77, v77, v111
	v_sub_u32_e32 v111, 0, v203
	v_max_i32_e32 v111, v203, v111
	v_cvt_f32_u32_e32 v111, v111
	v_exp_f32_e32 v77, v77
	v_cmp_ne_u32_e32 vcc, v134, v202
	v_mul_f32_e32 v111, v112, v111
	v_exp_f32_e32 v111, v111
	v_cndmask_b32_e32 v77, 2.0, v77, vcc
	v_cmp_ne_u32_e32 vcc, v134, v200
	v_mul_f32_e32 v97, v77, v97
	v_cndmask_b32_e64 v112, v108, v109, s[40:41]
	v_cndmask_b32_e32 v77, 2.0, v111, vcc
	v_sub_u32_e32 v111, 0, v201
	v_max_i32_e32 v111, v201, v111
	v_cvt_f32_u32_e32 v111, v111
	v_cmp_gt_i32_e32 vcc, 0, v201
	v_mul_f32_e32 v77, v77, v90
	v_cmp_gt_i32_e64 s[40:41], 0, v195
	v_cndmask_b32_e32 v90, v108, v109, vcc
	v_mul_f32_e32 v90, v90, v111
	v_sub_u32_e32 v111, 0, v199
	v_max_i32_e32 v111, v199, v111
	v_cvt_f32_u32_e32 v111, v111
	v_exp_f32_e32 v90, v90
	v_cmp_ne_u32_e32 vcc, v134, v198
	v_mul_f32_e32 v111, v112, v111
	v_exp_f32_e32 v111, v111
	v_cndmask_b32_e32 v90, 2.0, v90, vcc
	v_cmp_ne_u32_e32 vcc, v134, v196
	v_mul_f32_e32 v90, v90, v91
	v_cndmask_b32_e64 v112, v108, v109, s[40:41]
	v_cndmask_b32_e32 v91, 2.0, v111, vcc
	v_sub_u32_e32 v111, 0, v197
	v_max_i32_e32 v111, v197, v111
	v_cvt_f32_u32_e32 v111, v111
	v_cmp_gt_i32_e32 vcc, 0, v197
	v_mul_f32_e32 v91, v91, v92
	v_cmp_gt_i32_e64 s[40:41], 0, v174
	v_cndmask_b32_e32 v92, v108, v109, vcc
	v_mul_f32_e32 v92, v92, v111
	v_sub_u32_e32 v111, 0, v195
	v_max_i32_e32 v111, v195, v111
	v_cvt_f32_u32_e32 v111, v111
	v_exp_f32_e32 v92, v92
	v_cmp_ne_u32_e32 vcc, v134, v194
	v_mul_f32_e32 v111, v112, v111
	v_exp_f32_e32 v111, v111
	v_cndmask_b32_e32 v92, 2.0, v92, vcc
	v_cmp_ne_u32_e32 vcc, v134, v175
	v_mul_f32_e32 v92, v92, v93
	v_cndmask_b32_e64 v112, v108, v109, s[40:41]
	v_cndmask_b32_e32 v93, 2.0, v111, vcc
	v_sub_u32_e32 v111, 0, v193
	v_max_i32_e32 v111, v193, v111
	v_cvt_f32_u32_e32 v111, v111
	v_cmp_gt_i32_e32 vcc, 0, v193
	v_mul_f32_e32 v86, v93, v86
	v_cmp_gt_i32_e64 s[40:41], 0, v170
	v_cndmask_b32_e32 v93, v108, v109, vcc
	v_mul_f32_e32 v93, v93, v111
	v_sub_u32_e32 v111, 0, v174
	v_max_i32_e32 v111, v174, v111
	v_cvt_f32_u32_e32 v111, v111
	v_exp_f32_e32 v93, v93
	v_cmp_ne_u32_e32 vcc, v134, v173
	v_mul_f32_e32 v111, v112, v111
	v_exp_f32_e32 v111, v111
	v_cndmask_b32_e32 v93, 2.0, v93, vcc
	v_cmp_ne_u32_e32 vcc, v134, v171
	v_mul_f32_e32 v87, v93, v87
	v_cndmask_b32_e64 v112, v108, v109, s[40:41]
	v_cndmask_b32_e32 v93, 2.0, v111, vcc
	v_sub_u32_e32 v111, 0, v172
	v_max_i32_e32 v111, v172, v111
	v_cvt_f32_u32_e32 v111, v111
	v_cmp_gt_i32_e32 vcc, 0, v172
	v_mul_f32_e32 v88, v93, v88
	v_cmp_gt_i32_e64 s[40:41], 0, v166
	v_cndmask_b32_e32 v93, v108, v109, vcc
	v_mul_f32_e32 v93, v93, v111
	v_sub_u32_e32 v111, 0, v170
	v_max_i32_e32 v111, v170, v111
	v_cvt_f32_u32_e32 v111, v111
	v_exp_f32_e32 v93, v93
	v_cmp_ne_u32_e32 vcc, v134, v169
	v_mul_f32_e32 v111, v112, v111
	v_exp_f32_e32 v111, v111
	v_cndmask_b32_e32 v93, 2.0, v93, vcc
	v_cmp_ne_u32_e32 vcc, v134, v167
	v_mul_f32_e32 v89, v93, v89
	v_cndmask_b32_e64 v112, v108, v109, s[40:41]
	v_cndmask_b32_e32 v93, 2.0, v111, vcc
	v_sub_u32_e32 v111, 0, v168
	v_max_i32_e32 v111, v168, v111
	v_cvt_f32_u32_e32 v111, v111
	v_cmp_gt_i32_e32 vcc, 0, v168
	v_mul_f32_e32 v82, v93, v82
	v_cmp_gt_i32_e64 s[40:41], 0, v151
	v_cndmask_b32_e32 v93, v108, v109, vcc
	v_mul_f32_e32 v93, v93, v111
	v_sub_u32_e32 v111, 0, v166
	v_max_i32_e32 v111, v166, v111
	v_cvt_f32_u32_e32 v111, v111
	v_exp_f32_e32 v93, v93
	v_cmp_ne_u32_e32 vcc, v134, v164
	v_mul_f32_e32 v111, v112, v111
	v_exp_f32_e32 v111, v111
	v_cndmask_b32_e32 v93, 2.0, v93, vcc
	v_cmp_ne_u32_e32 vcc, v134, v163
	v_mul_f32_e32 v83, v93, v83
	v_cndmask_b32_e64 v112, v108, v109, s[40:41]
	v_cndmask_b32_e32 v93, 2.0, v111, vcc
	v_sub_u32_e32 v111, 0, v165
	v_max_i32_e32 v111, v165, v111
	v_cvt_f32_u32_e32 v111, v111
	v_cmp_gt_i32_e32 vcc, 0, v165
	v_mul_f32_e32 v84, v93, v84
	s_nop 0
	v_cndmask_b32_e32 v93, v108, v109, vcc
	v_mul_f32_e32 v93, v93, v111
	v_sub_u32_e32 v111, 0, v151
	v_max_i32_e32 v111, v151, v111
	v_cvt_f32_u32_e32 v111, v111
	v_exp_f32_e32 v93, v93
	v_cmp_ne_u32_e32 vcc, v134, v149
	v_mul_f32_e32 v111, v112, v111
	v_exp_f32_e32 v111, v111
	v_cndmask_b32_e32 v93, 2.0, v93, vcc
	v_cmp_ne_u32_e32 vcc, v134, v148
	v_mul_f32_e32 v85, v93, v85
	s_nop 0
	v_cndmask_b32_e32 v93, 2.0, v111, vcc
	v_sub_u32_e32 v111, 0, v150
	v_max_i32_e32 v111, v150, v111
	v_cvt_f32_u32_e32 v111, v111
	v_cmp_gt_i32_e32 vcc, 0, v150
	v_mul_f32_e32 v118, v93, v78
	v_sub_u32_e32 v93, v134, v147
	v_cndmask_b32_e32 v78, v108, v109, vcc
	v_mul_f32_e32 v78, v78, v111
	v_sub_u32_e32 v111, 0, v93
	v_max_i32_e32 v111, v93, v111
	v_cvt_f32_u32_e32 v111, v111
	v_cmp_gt_i32_e64 s[40:41], 0, v93
	v_exp_f32_e32 v78, v78
	v_cmp_ne_u32_e32 vcc, v134, v146
	v_cndmask_b32_e64 v93, v108, v109, s[40:41]
	v_mul_f32_e32 v93, v93, v111
	v_exp_f32_e32 v93, v93
	v_cndmask_b32_e32 v78, 2.0, v78, vcc
	v_mul_f32_e32 v119, v78, v79
	v_cmp_ne_u32_e32 vcc, v134, v147
	v_sub_u32_e32 v79, v134, v145
	s_nop 0
	v_cndmask_b32_e32 v78, 2.0, v93, vcc
	v_sub_u32_e32 v93, 0, v79
	v_max_i32_e32 v93, v79, v93
	v_cmp_gt_i32_e32 vcc, 0, v79
	v_sub_u32_e32 v79, v134, v144
	v_mul_f32_e32 v120, v78, v80
	v_sub_u32_e32 v80, 0, v79
	v_cvt_f32_u32_e32 v93, v93
	v_max_i32_e32 v80, v79, v80
	v_cvt_f32_u32_e32 v80, v80
	v_cndmask_b32_e32 v78, v108, v109, vcc
	v_cmp_gt_i32_e64 s[40:41], 0, v79
	v_mul_f32_e32 v78, v78, v93
	v_exp_f32_e32 v78, v78
	v_cndmask_b32_e64 v79, v108, v109, s[40:41]
	v_mul_f32_e32 v79, v79, v80
	v_exp_f32_e32 v79, v79
	v_cmp_ne_u32_e32 vcc, v134, v145
	s_nop 1
	v_cndmask_b32_e32 v78, 2.0, v78, vcc
	v_cmp_ne_u32_e32 vcc, v134, v144
	v_mul_f32_e32 v121, v78, v81
	s_nop 0
	v_cndmask_b32_e32 v78, 2.0, v79, vcc
	v_sub_u32_e32 v79, v134, v143
	v_sub_u32_e32 v80, 0, v79
	v_max_i32_e32 v80, v79, v80
	v_mul_f32_e32 v122, v78, v70
	v_sub_u32_e32 v78, v134, v142
	v_cvt_f32_u32_e32 v80, v80
	v_cmp_gt_i32_e32 vcc, 0, v79
	v_sub_u32_e32 v79, 0, v78
	v_max_i32_e32 v79, v78, v79
	v_cvt_f32_u32_e32 v79, v79
	v_cndmask_b32_e32 v70, v108, v109, vcc
	v_mul_f32_e32 v70, v70, v80
	v_cmp_gt_i32_e64 s[40:41], 0, v78
	v_exp_f32_e32 v70, v70
	v_cmp_ne_u32_e32 vcc, v134, v143
	v_cndmask_b32_e64 v78, v108, v109, s[40:41]
	v_mul_f32_e32 v78, v78, v79
	v_exp_f32_e32 v78, v78
	v_cndmask_b32_e32 v70, 2.0, v70, vcc
	v_mul_f32_e32 v123, v70, v71
	v_cmp_ne_u32_e32 vcc, v134, v142
	v_sub_u32_e32 v71, v134, v133
	s_nop 0
	v_cndmask_b32_e32 v70, 2.0, v78, vcc
	v_sub_u32_e32 v78, 0, v71
	v_max_i32_e32 v78, v71, v78
	v_cmp_gt_i32_e32 vcc, 0, v71
	v_sub_u32_e32 v71, v134, v132
	v_mul_f32_e32 v124, v70, v72
	v_sub_u32_e32 v72, 0, v71
	v_cvt_f32_u32_e32 v78, v78
	v_max_i32_e32 v72, v71, v72
	v_cvt_f32_u32_e32 v72, v72
	v_cndmask_b32_e32 v70, v108, v109, vcc
	v_cmp_gt_i32_e64 s[40:41], 0, v71
	v_mul_f32_e32 v70, v70, v78
	v_exp_f32_e32 v70, v70
	v_cndmask_b32_e64 v71, v108, v109, s[40:41]
	v_mul_f32_e32 v71, v71, v72
	v_exp_f32_e32 v71, v71
	v_cmp_ne_u32_e32 vcc, v134, v133
	s_nop 1
	v_cndmask_b32_e32 v70, 2.0, v70, vcc
	v_cmp_ne_u32_e32 vcc, v134, v132
	v_mul_f32_e32 v125, v70, v73
	s_nop 0
	v_cndmask_b32_e32 v70, 2.0, v71, vcc
	v_sub_u32_e32 v71, v134, v131
	v_sub_u32_e32 v72, 0, v71
	v_max_i32_e32 v72, v71, v72
	v_cvt_f32_u32_e32 v72, v72
	v_cmp_gt_i32_e32 vcc, 0, v71
	v_mul_f32_e32 v126, v70, v66
	v_cvt_pk_bf16_f32 v70, v110, v74
	v_cvt_pk_bf16_f32 v71, v75, v76
	s_nop 0
	v_cndmask_b32_e32 v66, v108, v109, vcc
	v_mul_f32_e32 v66, v66, v72
	v_exp_f32_e32 v66, v66
	v_cmp_ne_u32_e32 vcc, v134, v131
	v_cvt_pk_bf16_f32 v72, v94, v95
	v_cvt_pk_bf16_f32 v73, v96, v97
	ds_read_b64_tr_b16 v[80:81], v128 offset:20736
	ds_read_b64_tr_b16 v[78:79], v128 offset:18432
	v_cndmask_b32_e32 v66, 2.0, v66, vcc
	v_mul_f32_e32 v127, v66, v67
	v_sub_u32_e32 v66, v134, v130
	v_sub_u32_e32 v67, 0, v66
	v_max_i32_e32 v67, v66, v67
	ds_read_b64_tr_b16 v[94:95], v128 offset:18464
	ds_read_b64_tr_b16 v[96:97], v128 offset:20768
	v_cvt_f32_u32_e32 v67, v67
	ds_read_b64_tr_b16 v[110:111], v128 offset:18496
	ds_read_b64_tr_b16 v[112:113], v128 offset:20800
	ds_read_b64_tr_b16 v[114:115], v128 offset:18528
	ds_read_b64_tr_b16 v[116:117], v128 offset:20832
	v_cmp_gt_i32_e32 vcc, 0, v66
	v_cvt_pk_bf16_f32 v74, v77, v90
	v_cvt_pk_bf16_f32 v75, v91, v92
	v_cvt_pk_bf16_f32 v76, v86, v87
	v_cvt_pk_bf16_f32 v77, v88, v89
	ds_read_b64_tr_b16 v[88:89], v128 offset:25344
	ds_read_b64_tr_b16 v[86:87], v128 offset:23040
	v_cndmask_b32_e32 v66, v108, v109, vcc
	s_waitcnt lgkmcnt(8)
	v_mfma_f32_16x16x32_bf16 v[78:81], v[78:81], v[70:73], 0
	v_mul_f32_e32 v66, v66, v67
	v_exp_f32_e32 v66, v66
	v_sub_u32_e32 v67, v134, v129
	s_waitcnt lgkmcnt(4)
	v_mfma_f32_16x16x32_bf16 v[90:93], v[110:113], v[70:73], 0
	ds_read_b64_tr_b16 v[110:111], v128 offset:23072
	ds_read_b64_tr_b16 v[112:113], v128 offset:25376
	v_cmp_ne_u32_e32 vcc, v134, v130
	v_mfma_f32_16x16x32_bf16 v[94:97], v[94:97], v[70:73], 0
	s_nop 0
	v_cndmask_b32_e32 v66, 2.0, v66, vcc
	v_cmp_gt_i32_e32 vcc, 0, v67
	s_waitcnt lgkmcnt(2)
	v_mfma_f32_16x16x32_bf16 v[78:81], v[86:89], v[74:77], v[78:81]
	v_sub_u32_e32 v86, 0, v67
	v_max_i32_e32 v67, v67, v86
	v_cvt_f32_u32_e32 v67, v67
	s_waitcnt lgkmcnt(0)
	v_mfma_f32_16x16x32_bf16 v[86:89], v[110:113], v[74:77], v[94:97]
	s_nop 2
	ds_read_b64_tr_b16 v[94:95], v128 offset:23104
	ds_read_b64_tr_b16 v[96:97], v128 offset:25408
	ds_read_b64_tr_b16 v[110:111], v128 offset:23136
	ds_read_b64_tr_b16 v[112:113], v128 offset:25440
	v_cvt_pk_bf16_f32 v82, v82, v83
	v_cvt_pk_bf16_f32 v83, v84, v85
	v_mfma_f32_16x16x32_bf16 v[70:73], v[114:117], v[70:73], 0
	v_cvt_pk_bf16_f32 v84, v118, v119
	v_cvt_pk_bf16_f32 v85, v120, v121
	ds_read_b64_tr_b16 v[116:117], v128 offset:29952
	ds_read_b64_tr_b16 v[114:115], v128 offset:27648
	s_waitcnt lgkmcnt(2)
	v_mfma_f32_16x16x32_bf16 v[70:73], v[110:113], v[74:77], v[70:73]
	v_cndmask_b32_e32 v110, v108, v109, vcc
	v_mul_f32_e32 v67, v110, v67
	v_exp_f32_e32 v67, v67
	v_mfma_f32_16x16x32_bf16 v[90:93], v[94:97], v[74:77], v[90:93]
	ds_read_b64_tr_b16 v[94:95], v128 offset:27680
	ds_read_b64_tr_b16 v[96:97], v128 offset:29984
	ds_read_b64_tr_b16 v[74:75], v128 offset:27712
	ds_read_b64_tr_b16 v[76:77], v128 offset:30016
	v_cmp_ne_u32_e32 vcc, v134, v129
	v_mul_f32_e32 v110, v66, v68
	s_waitcnt lgkmcnt(2)
	v_mfma_f32_16x16x32_bf16 v[86:89], v[94:97], v[82:85], v[86:89]
	v_cndmask_b32_e32 v66, 2.0, v67, vcc
	v_mul_f32_e32 v94, v66, v69
	s_waitcnt lgkmcnt(0)
	v_mfma_f32_16x16x32_bf16 v[66:69], v[74:77], v[82:85], v[90:93]
	ds_read_b64_tr_b16 v[74:75], v128 offset:27744
	ds_read_b64_tr_b16 v[76:77], v128 offset:30048
	v_cvt_pk_bf16_f32 v90, v122, v123
	v_cvt_pk_bf16_f32 v91, v124, v125
	v_mfma_f32_16x16x32_bf16 v[78:81], v[114:117], v[82:85], v[78:81]
	v_cvt_pk_bf16_f32 v92, v126, v127
	v_cvt_pk_bf16_f32 v93, v110, v94
	ds_read_b64_tr_b16 v[96:97], v128 offset:34560
	ds_read_b64_tr_b16 v[94:95], v128 offset:32256
	s_waitcnt lgkmcnt(2)
	v_mfma_f32_16x16x32_bf16 v[70:73], v[74:77], v[82:85], v[70:73]
	ds_read_b64_tr_b16 v[74:75], v128 offset:32288
	ds_read_b64_tr_b16 v[76:77], v128 offset:34592
	ds_read_b64_tr_b16 v[82:83], v128 offset:32320
	ds_read_b64_tr_b16 v[84:85], v128 offset:34624
	s_waitcnt lgkmcnt(0)
	v_mfma_f32_16x16x32_bf16 v[66:69], v[82:85], v[90:93], v[66:69]
	v_mul_f32_e32 v82, v108, v139
	v_exp_f32_e32 v82, v82
	v_mul_f32_e32 v83, v109, v141
	v_mfma_f32_16x16x32_bf16 v[78:81], v[94:97], v[90:93], v[78:81]
	v_exp_f32_e32 v84, v83
	s_nop 2
	v_pk_fma_f32 v[40:41], v[82:83], v[40:41], v[68:69] op_sel_hi:[0,1,1]
	v_pk_fma_f32 v[38:39], v[82:83], v[38:39], v[66:67] op_sel_hi:[0,1,1]
	v_mfma_f32_16x16x32_bf16 v[74:77], v[74:77], v[90:93], v[86:89]
	s_nop 2
	ds_read_b64_tr_b16 v[86:87], v128 offset:32352
	ds_read_b64_tr_b16 v[88:89], v128 offset:34656
	v_pk_fma_f32 v[36:37], v[82:83], v[36:37], v[80:81] op_sel_hi:[0,1,1]
	v_pk_fma_f32 v[34:35], v[82:83], v[34:35], v[78:79] op_sel_hi:[0,1,1]
	s_waitcnt lgkmcnt(0)
	v_mfma_f32_16x16x32_bf16 v[70:73], v[86:89], v[90:93], v[70:73]
	v_fma_f32 v36, v84, v52, v36
	v_fma_f32 v37, v84, v53, v37
	v_pk_fma_f32 v[34:35], v[84:85], v[50:51], v[34:35] op_sel_hi:[0,1,1]
	v_pk_fma_f32 v[48:49], v[82:83], v[48:49], v[76:77] op_sel_hi:[0,1,1]
	v_pk_fma_f32 v[46:47], v[82:83], v[46:47], v[74:75] op_sel_hi:[0,1,1]
	v_add_f32_e32 v50, v34, v35
	v_add_f32_e32 v51, v36, v37
	v_pk_fma_f32 v[48:49], v[84:85], v[64:65], v[48:49] op_sel_hi:[0,1,1]
	v_pk_fma_f32 v[46:47], v[84:85], v[62:63], v[46:47] op_sel_hi:[0,1,1]
	v_add_f32_e32 v50, v50, v51
	v_add_f32_e32 v51, v46, v47
	v_add_f32_e32 v52, v48, v49
	v_add_f32_e32 v50, 0, v50
	v_add_f32_e32 v51, v51, v52
	v_pk_fma_f32 v[40:41], v[84:85], v[56:57], v[40:41] op_sel_hi:[0,1,1]
	v_pk_fma_f32 v[38:39], v[84:85], v[54:55], v[38:39] op_sel_hi:[0,1,1]
	v_add_f32_e32 v50, v50, v51
	v_add_f32_e32 v51, v38, v39
	v_add_f32_e32 v52, v40, v41
	v_pk_fma_f32 v[44:45], v[82:83], v[44:45], v[72:73] op_sel_hi:[0,1,1]
	v_pk_fma_f32 v[42:43], v[82:83], v[42:43], v[70:71] op_sel_hi:[0,1,1]
	v_add_f32_e32 v51, v51, v52
	v_pk_fma_f32 v[44:45], v[84:85], v[60:61], v[44:45] op_sel_hi:[0,1,1]
	v_pk_fma_f32 v[42:43], v[84:85], v[58:59], v[42:43] op_sel_hi:[0,1,1]
	v_add_f32_e32 v50, v50, v51
	v_add_f32_e32 v51, v42, v43
	v_add_f32_e32 v52, v44, v45
	v_add_f32_e32 v51, v51, v52
	v_add_f32_e32 v50, v50, v51
	v_mov_b32_e32 v51, v50
	s_nop 1
	v_permlane16_swap_b32_e32 v50, v51
	v_add_f32_e32 v50, v50, v51
	v_mov_b32_e32 v51, v50
	s_nop 1
	v_permlane32_swap_b32_e32 v50, v51
	v_add_f32_e32 v50, v50, v51
	v_fmac_f32_e32 v37, 0xbc800000, v50
	v_fmac_f32_e32 v35, 0xbc800000, v50
	v_fmamk_f32 v36, v50, 0xbc800000, v36
	v_fmamk_f32 v34, v50, 0xbc800000, v34
	v_mul_f32_e32 v51, v35, v35
	v_mul_f32_e32 v52, v37, v37
	v_fmac_f32_e32 v51, v34, v34
	v_fmac_f32_e32 v52, v36, v36
	v_fmac_f32_e32 v49, 0xbc800000, v50
	v_fmac_f32_e32 v47, 0xbc800000, v50
	v_add_f32_e32 v51, v51, v52
	v_fmamk_f32 v48, v50, 0xbc800000, v48
	v_fmamk_f32 v46, v50, 0xbc800000, v46
	v_mul_f32_e32 v52, v47, v47
	v_mul_f32_e32 v53, v49, v49
	v_fmac_f32_e32 v52, v46, v46
	v_fmac_f32_e32 v53, v48, v48
	v_add_f32_e32 v52, v52, v53
	v_fmac_f32_e32 v41, 0xbc800000, v50
	v_fmac_f32_e32 v39, 0xbc800000, v50
	v_add_f32_e32 v51, v51, v52
	v_fmamk_f32 v40, v50, 0xbc800000, v40
	v_fmamk_f32 v38, v50, 0xbc800000, v38
	v_mul_f32_e32 v52, v39, v39
	v_mul_f32_e32 v53, v41, v41
	v_fmac_f32_e32 v52, v38, v38
	v_fmac_f32_e32 v53, v40, v40
	v_add_f32_e32 v52, v52, v53
	v_fmac_f32_e32 v45, 0xbc800000, v50
	v_fmac_f32_e32 v43, 0xbc800000, v50
	v_add_f32_e32 v51, v52, v51
	v_fmamk_f32 v44, v50, 0xbc800000, v44
	v_fmamk_f32 v42, v50, 0xbc800000, v42
	v_mul_f32_e32 v50, v43, v43
	v_mul_f32_e32 v52, v45, v45
	v_fmac_f32_e32 v50, v42, v42
	v_fmac_f32_e32 v52, v44, v44
	v_add_f32_e32 v50, v50, v52
	v_add_f32_e32 v50, v50, v51
	v_mov_b32_e32 v51, v50
	s_nop 1
	v_permlane16_swap_b32_e32 v50, v51
	v_add_f32_e32 v50, v50, v51
	v_mov_b32_e32 v51, v50
	s_nop 1
	v_permlane32_swap_b32_e32 v50, v51
	v_add_f32_e32 v50, v50, v51
	v_fmamk_f32 v50, v50, 0x3c800000, v177
	v_rsq_f32_e32 v50, v50
	v_lshlrev_b64 v[52:53], 11, v[98:99]
	s_waitcnt vmcnt(3)
	v_lshlrev_b32_e32 v54, 16, v104
	v_and_b32_e32 v55, 0xffff0000, v104
	v_pk_mul_f32 v[36:37], v[36:37], v[50:51] op_sel_hi:[1,0]
	v_pk_mul_f32 v[34:35], v[34:35], v[50:51] op_sel_hi:[1,0]
	v_lshlrev_b32_e32 v56, 16, v105
	v_and_b32_e32 v57, 0xffff0000, v105
	v_pk_mul_f32 v[30:31], v[30:31], v[34:35]
	v_pk_mul_f32 v[32:33], v[32:33], v[36:37]
	v_lshl_add_u64 v[52:53], s[70:71], 0, v[52:53]
	v_pk_mul_f32 v[32:33], v[32:33], v[56:57]
	v_pk_mul_f32 v[30:31], v[30:31], v[54:55]
	v_pk_mul_f32 v[46:47], v[46:47], v[50:51] op_sel_hi:[1,0]
	v_cvt_pk_bf16_f32 v30, v30, v31
	v_cvt_pk_bf16_f32 v31, v32, v33
	v_lshl_add_u64 v[32:33], v[52:53], 0, v[0:1]
	global_store_dwordx2 v[32:33], v[30:31], off
	s_waitcnt vmcnt(3)
	v_lshlrev_b32_e32 v30, 16, v106
	v_and_b32_e32 v31, 0xffff0000, v106
	v_pk_mul_f32 v[36:37], v[48:49], v[50:51] op_sel_hi:[1,0]
	v_pk_mul_f32 v[26:27], v[26:27], v[46:47]
	v_lshlrev_b32_e32 v34, 16, v107
	v_and_b32_e32 v35, 0xffff0000, v107
	v_pk_mul_f32 v[28:29], v[28:29], v[36:37]
	v_pk_mul_f32 v[26:27], v[26:27], v[30:31]
	v_pk_mul_f32 v[28:29], v[28:29], v[34:35]
	v_cvt_pk_bf16_f32 v26, v26, v27
	v_pk_mul_f32 v[34:35], v[38:39], v[50:51] op_sel_hi:[1,0]
	v_cvt_pk_bf16_f32 v27, v28, v29
	global_store_dwordx2 v[32:33], v[26:27], off offset:32
	s_waitcnt vmcnt(3)
	v_lshlrev_b32_e32 v26, 16, v102
	v_and_b32_e32 v27, 0xffff0000, v102
	v_pk_mul_f32 v[30:31], v[40:41], v[50:51] op_sel_hi:[1,0]
	v_pk_mul_f32 v[22:23], v[22:23], v[34:35]
	v_lshlrev_b32_e32 v28, 16, v103
	v_and_b32_e32 v29, 0xffff0000, v103
	v_pk_mul_f32 v[24:25], v[24:25], v[30:31]
	v_pk_mul_f32 v[22:23], v[22:23], v[26:27]
	v_pk_mul_f32 v[24:25], v[24:25], v[28:29]
	v_cvt_pk_bf16_f32 v22, v22, v23
	v_pk_mul_f32 v[28:29], v[42:43], v[50:51] op_sel_hi:[1,0]
	v_cvt_pk_bf16_f32 v23, v24, v25
	global_store_dwordx2 v[32:33], v[22:23], off offset:64
	s_waitcnt vmcnt(3)
	v_lshlrev_b32_e32 v22, 16, v100
	v_and_b32_e32 v23, 0xffff0000, v100
	v_pk_mul_f32 v[26:27], v[44:45], v[50:51] op_sel_hi:[1,0]
	v_pk_mul_f32 v[18:19], v[18:19], v[28:29]
	v_lshlrev_b32_e32 v24, 16, v101
	v_and_b32_e32 v25, 0xffff0000, v101
	v_pk_mul_f32 v[20:21], v[20:21], v[26:27]
	v_pk_mul_f32 v[18:19], v[18:19], v[22:23]
	v_pk_mul_f32 v[20:21], v[20:21], v[24:25]
	v_cvt_pk_bf16_f32 v18, v18, v19
	s_nop 0
	v_cvt_pk_bf16_f32 v19, v20, v21
	global_store_dwordx2 v[32:33], v[18:19], off offset:96
	s_barrier
.LBB0_46:
	v_readlane_b32 s2, v253, 34
	v_readlane_b32 s74, v254, 59
	v_readlane_b32 s82, v254, 61
	s_cmp_ge_i32 s2, s15
	v_readlane_b32 s75, v254, 60
	v_readlane_b32 s83, v254, 62
	s_cbranch_scc1 .LBB0_48
	v_readlane_b32 s2, v253, 32
	v_readlane_b32 s3, v253, 33
	s_waitcnt vmcnt(4)
	v_mov_b64_e32 v[18:19], s[72:73]
	v_mov_b32_e32 v137, v1
	v_lshl_add_u64 v[86:87], s[2:3], 0, v[134:135]
	v_readlane_b32 s2, v253, 7
	s_lshl_b32 s2, s2, 2
	v_cmp_gt_i32_e32 vcc, 0, v217
	v_mov_b32_e32 v0, s2
	v_mad_u64_u32 v[18:19], s[2:3], v86, s64, v[18:19]
	v_readlane_b32 s2, v253, 8
	v_mad_i32_i24 v19, v87, s64, v19
	s_lshl_b32 s16, s2, 1
	v_lshl_add_u64 v[20:21], v[18:19], 0, s[16:17]
	v_lshl_add_u64 v[20:21], v[20:21], 0, v[136:137]
	global_load_dword v97, v0, s[28:29]
	global_load_dword v96, v0, s[28:29] offset:16
	global_load_dwordx4 v[74:77], v[20:21], off
	global_load_dwordx4 v[50:53], v[20:21], off offset:64
	v_readlane_b32 s2, v253, 35
	v_readlane_b32 s3, v253, 36
	s_add_u32 s2, s42, s2
	s_addc_u32 s3, s43, s3
	s_add_u32 s10, s2, 0x2000
	s_addc_u32 s11, s3, 0
	s_nop 0
	global_load_dwordx4 v[34:37], v159, s[2:3]
	global_load_dwordx4 v[38:41], v159, s[10:11]
	global_load_dwordx4 v[54:57], v159, s[2:3] offset:64
	global_load_dwordx4 v[58:61], v162, s[10:11]
	global_load_dwordx4 v[62:65], v159, s[2:3] offset:2048
	global_load_dwordx4 v[66:69], v161, s[10:11]
	global_load_dwordx4 v[70:73], v159, s[2:3] offset:2112
	global_load_dwordx4 v[78:81], v160, s[10:11]
	global_load_dwordx4 v[82:85], v158, s[2:3]
	global_load_dwordx4 v[98:101], v158, s[10:11]
	global_load_dwordx4 v[102:105], v157, s[2:3]
	global_load_dwordx4 v[106:109], v157, s[10:11]
	global_load_dwordx4 v[110:113], v156, s[2:3]
	global_load_dwordx4 v[114:117], v156, s[10:11]
	global_load_dwordx4 v[42:45], v155, s[2:3]
	global_load_dwordx4 v[46:49], v155, s[10:11]
	v_lshlrev_b32_e32 v0, 1, v154
	v_lshl_add_u64 v[18:19], v[18:19], 0, v[0:1]
	v_lshlrev_b32_e32 v20, 2, v154
	global_load_dwordx2 v[94:95], v[18:19], off offset:1536
	global_load_dwordx4 v[30:33], v20, s[44:45]
	global_load_dwordx2 v[92:93], v[18:19], off offset:1568
	global_load_dwordx4 v[26:29], v20, s[44:45] offset:64
	global_load_dwordx2 v[90:91], v[18:19], off offset:1600
	global_load_dwordx4 v[22:25], v20, s[44:45] offset:128
	global_load_dwordx2 v[88:89], v[18:19], off offset:1632
	s_nop 0
	global_load_dwordx4 v[18:21], v20, s[44:45] offset:192
	s_waitcnt vmcnt(30)
	ds_write_b128 v153, v[6:9]
	ds_write_b128 v153, v[2:5] offset:16
	s_waitcnt vmcnt(28)
	ds_write_b128 v153, v[14:17] offset:18432
	ds_write_b128 v153, v[10:13] offset:18448
	s_waitcnt lgkmcnt(0)
	s_barrier
	s_waitcnt vmcnt(23)
	v_mfma_f32_16x16x32_bf16 v[2:5], v[34:37], v[74:77], 0
	s_waitcnt vmcnt(22)
	v_mfma_f32_16x16x32_bf16 v[10:13], v[38:41], v[74:77], 0
	s_waitcnt vmcnt(21)
	v_mfma_f32_16x16x32_bf16 v[6:9], v[54:57], v[50:53], v[2:5]
	s_waitcnt vmcnt(20)
	v_mfma_f32_16x16x32_bf16 v[2:5], v[58:61], v[50:53], v[10:13]
	s_waitcnt vmcnt(19)
	v_mfma_f32_16x16x32_bf16 v[10:13], v[62:65], v[74:77], 0
	s_waitcnt vmcnt(18)
	v_mfma_f32_16x16x32_bf16 v[34:37], v[66:69], v[74:77], 0
	s_waitcnt vmcnt(17)
	v_mfma_f32_16x16x32_bf16 v[14:17], v[70:73], v[50:53], v[10:13]
	s_waitcnt vmcnt(16)
	v_mfma_f32_16x16x32_bf16 v[10:13], v[78:81], v[50:53], v[34:37]
	s_waitcnt vmcnt(15)
	v_mfma_f32_16x16x32_bf16 v[34:37], v[82:85], v[74:77], 0
	s_waitcnt vmcnt(14)
	v_mfma_f32_16x16x32_bf16 v[54:57], v[98:101], v[74:77], 0
	s_waitcnt vmcnt(13)
	v_mfma_f32_16x16x32_bf16 v[38:41], v[102:105], v[50:53], v[34:37]
	s_waitcnt vmcnt(12)
	v_mfma_f32_16x16x32_bf16 v[34:37], v[106:109], v[50:53], v[54:57]
	s_waitcnt vmcnt(11)
	v_mfma_f32_16x16x32_bf16 v[54:57], v[110:113], v[74:77], 0
	s_waitcnt vmcnt(10)
	v_mfma_f32_16x16x32_bf16 v[58:61], v[114:117], v[74:77], 0
	s_waitcnt vmcnt(9)
	v_mfma_f32_16x16x32_bf16 v[42:45], v[42:45], v[50:53], v[54:57]
	s_waitcnt vmcnt(8)
	v_mfma_f32_16x16x32_bf16 v[46:49], v[46:49], v[50:53], v[58:61]
	s_nop 1
	ds_read_b128 v[54:57], v218
	ds_read_b128 v[98:101], v218 offset:13888
	ds_read_b128 v[58:61], v218 offset:64
	s_waitcnt lgkmcnt(2)
	v_mfma_f32_16x16x32_bf16 v[54:57], v[54:57], v[74:77], 0
	s_waitcnt lgkmcnt(0)
	v_mfma_f32_16x16x32_bf16 v[82:85], v[58:61], v[50:53], v[54:57]
	ds_read_b128 v[58:61], v218 offset:2368
	s_nop 4
	ds_read_b128 v[54:57], v218 offset:2304
	s_waitcnt lgkmcnt(0)
	v_mfma_f32_16x16x32_bf16 v[54:57], v[54:57], v[74:77], 0
	v_mfma_f32_16x16x32_bf16 v[78:81], v[58:61], v[50:53], v[54:57]
	ds_read_b128 v[58:61], v218 offset:4672
	s_nop 5
	ds_read_b128 v[54:57], v218 offset:4608
	s_waitcnt lgkmcnt(0)
	v_mfma_f32_16x16x32_bf16 v[54:57], v[54:57], v[74:77], 0
	v_mfma_f32_16x16x32_bf16 v[70:73], v[58:61], v[50:53], v[54:57]
	ds_read_b128 v[58:61], v218 offset:6976
	s_nop 5
	ds_read_b128 v[54:57], v218 offset:6912
	s_waitcnt lgkmcnt(0)
	v_mfma_f32_16x16x32_bf16 v[54:57], v[54:57], v[74:77], 0
	v_mfma_f32_16x16x32_bf16 v[66:69], v[58:61], v[50:53], v[54:57]
	ds_read_b128 v[58:61], v218 offset:9280
	s_nop 5
	ds_read_b128 v[54:57], v218 offset:9216
	s_waitcnt lgkmcnt(0)
	v_mfma_f32_16x16x32_bf16 v[54:57], v[54:57], v[74:77], 0
	v_mfma_f32_16x16x32_bf16 v[62:65], v[58:61], v[50:53], v[54:57]
	ds_read_b128 v[58:61], v218 offset:11584
	s_nop 5
	ds_read_b128 v[54:57], v218 offset:11520
	s_waitcnt lgkmcnt(0)
	v_mfma_f32_16x16x32_bf16 v[54:57], v[54:57], v[74:77], 0
	v_mfma_f32_16x16x32_bf16 v[58:61], v[58:61], v[50:53], v[54:57]
	s_nop 6
	ds_read_b128 v[54:57], v218 offset:13824
	s_waitcnt lgkmcnt(0)
	v_mfma_f32_16x16x32_bf16 v[54:57], v[54:57], v[74:77], 0
	v_mfma_f32_16x16x32_bf16 v[54:57], v[98:101], v[50:53], v[54:57]
	ds_read_b128 v[98:101], v218 offset:16128
	s_waitcnt lgkmcnt(0)
	v_mfma_f32_16x16x32_bf16 v[74:77], v[98:101], v[74:77], 0
	ds_read_b128 v[98:101], v218 offset:16192
	s_waitcnt lgkmcnt(0)
	v_mfma_f32_16x16x32_bf16 v[50:53], v[98:101], v[50:53], v[74:77]
	s_nop 4
	v_sub_u32_e32 v74, 0, v217
	v_max_i32_e32 v74, v217, v74
	v_cvt_f32_u32_e32 v74, v74
	v_cndmask_b32_e32 v75, v97, v96, vcc
	v_cmp_ne_u32_e32 vcc, v134, v152
	v_mul_f32_e32 v74, v75, v74
	v_exp_f32_e32 v74, v74
	v_sub_u32_e32 v75, 0, v216
	v_max_i32_e32 v75, v216, v75
	v_cvt_f32_u32_e32 v75, v75
	v_cndmask_b32_e32 v74, 2.0, v74, vcc
	v_cmp_gt_i32_e32 vcc, 0, v216
	v_mul_f32_e32 v74, v74, v82
	s_nop 0
	v_cndmask_b32_e32 v76, v97, v96, vcc
	v_mul_f32_e32 v75, v76, v75
	v_exp_f32_e32 v75, v75
	v_sub_u32_e32 v76, 0, v215
	v_max_i32_e32 v76, v215, v76
	v_cvt_f32_u32_e32 v76, v76
	v_cmp_ne_u32_e32 vcc, v134, v214
	s_nop 1
	v_cndmask_b32_e32 v75, 2.0, v75, vcc
	v_cmp_gt_i32_e32 vcc, 0, v215
	v_mul_f32_e32 v75, v75, v83
	s_nop 0
	v_cndmask_b32_e32 v77, v97, v96, vcc
	v_mul_f32_e32 v76, v77, v76
	v_exp_f32_e32 v76, v76
	v_sub_u32_e32 v77, 0, v213
	v_max_i32_e32 v77, v213, v77
	v_cvt_f32_u32_e32 v77, v77
	v_cmp_ne_u32_e32 vcc, v134, v212
	s_nop 1
	v_cndmask_b32_e32 v76, 2.0, v76, vcc
	v_cmp_gt_i32_e32 vcc, 0, v213
	v_mul_f32_e32 v76, v76, v84
	s_nop 0
	v_cndmask_b32_e32 v82, v97, v96, vcc
	v_mul_f32_e32 v77, v82, v77
	v_exp_f32_e32 v77, v77
	v_sub_u32_e32 v82, 0, v211
	v_max_i32_e32 v82, v211, v82
	v_cvt_f32_u32_e32 v82, v82
	v_cmp_ne_u32_e32 vcc, v134, v210
	s_nop 1
	v_cndmask_b32_e32 v77, 2.0, v77, vcc
	v_cmp_gt_i32_e32 vcc, 0, v211
	v_mul_f32_e32 v77, v77, v85
	s_nop 0
	v_cndmask_b32_e32 v83, v97, v96, vcc
	v_mul_f32_e32 v82, v83, v82
	v_exp_f32_e32 v82, v82
	v_cmp_ne_u32_e32 vcc, v134, v208
	s_nop 1
	v_cndmask_b32_e32 v82, 2.0, v82, vcc
	v_mul_f32_e32 v78, v82, v78
	v_sub_u32_e32 v82, 0, v209
	v_max_i32_e32 v82, v209, v82
	v_cvt_f32_u32_e32 v82, v82
	v_cmp_gt_i32_e32 vcc, 0, v209
	s_nop 1
	v_cndmask_b32_e32 v83, v97, v96, vcc
	v_mul_f32_e32 v82, v83, v82
	v_exp_f32_e32 v82, v82
	v_cmp_ne_u32_e32 vcc, v134, v206
	s_nop 1
	v_cndmask_b32_e32 v82, 2.0, v82, vcc
	v_mul_f32_e32 v79, v82, v79
	v_sub_u32_e32 v82, 0, v207
	v_max_i32_e32 v82, v207, v82
	v_cvt_f32_u32_e32 v82, v82
	v_cmp_gt_i32_e32 vcc, 0, v207
	s_nop 1
	v_cndmask_b32_e32 v83, v97, v96, vcc
	v_mul_f32_e32 v82, v83, v82
	v_exp_f32_e32 v82, v82
	v_cmp_ne_u32_e32 vcc, v134, v204
	s_nop 1
	v_cndmask_b32_e32 v82, 2.0, v82, vcc
	v_mul_f32_e32 v80, v82, v80
	v_sub_u32_e32 v82, 0, v205
	v_max_i32_e32 v82, v205, v82
	v_cvt_f32_u32_e32 v82, v82
	v_cmp_gt_i32_e32 vcc, 0, v205
	s_nop 1
	v_cndmask_b32_e32 v83, v97, v96, vcc
	v_mul_f32_e32 v82, v83, v82
	v_exp_f32_e32 v82, v82
	v_cmp_ne_u32_e32 vcc, v134, v202
	s_nop 1
	v_cndmask_b32_e32 v82, 2.0, v82, vcc
	v_mul_f32_e32 v81, v82, v81
	v_sub_u32_e32 v82, 0, v203
	v_max_i32_e32 v82, v203, v82
	v_cvt_f32_u32_e32 v82, v82
	v_cmp_gt_i32_e32 vcc, 0, v203
	s_nop 1
	v_cndmask_b32_e32 v83, v97, v96, vcc
	v_mul_f32_e32 v82, v83, v82
	v_exp_f32_e32 v82, v82
	v_cmp_ne_u32_e32 vcc, v134, v200
	s_nop 1
	v_cndmask_b32_e32 v82, 2.0, v82, vcc
	v_mul_f32_e32 v70, v82, v70
	v_sub_u32_e32 v82, 0, v201
	v_max_i32_e32 v82, v201, v82
	v_cvt_f32_u32_e32 v82, v82
	v_cmp_gt_i32_e32 vcc, 0, v201
	s_nop 1
	v_cndmask_b32_e32 v83, v97, v96, vcc
	v_mul_f32_e32 v82, v83, v82
	v_exp_f32_e32 v82, v82
	v_cmp_ne_u32_e32 vcc, v134, v198
	s_nop 1
	v_cndmask_b32_e32 v82, 2.0, v82, vcc
	v_mul_f32_e32 v71, v82, v71
	v_sub_u32_e32 v82, 0, v199
	v_max_i32_e32 v82, v199, v82
	v_cvt_f32_u32_e32 v82, v82
	v_cmp_gt_i32_e32 vcc, 0, v199
	s_nop 1
	v_cndmask_b32_e32 v83, v97, v96, vcc
	v_mul_f32_e32 v82, v83, v82
	v_exp_f32_e32 v82, v82
	v_cmp_ne_u32_e32 vcc, v134, v196
	s_nop 1
	v_cndmask_b32_e32 v82, 2.0, v82, vcc
	v_mul_f32_e32 v72, v82, v72
	v_sub_u32_e32 v82, 0, v197
	v_max_i32_e32 v82, v197, v82
	v_cvt_f32_u32_e32 v82, v82
	v_cmp_gt_i32_e32 vcc, 0, v197
	s_nop 1
	v_cndmask_b32_e32 v83, v97, v96, vcc
	v_mul_f32_e32 v82, v83, v82
	v_exp_f32_e32 v82, v82
	v_cmp_ne_u32_e32 vcc, v134, v194
	s_nop 1
	v_cndmask_b32_e32 v82, 2.0, v82, vcc
	v_mul_f32_e32 v73, v82, v73
	v_sub_u32_e32 v82, 0, v195
	v_max_i32_e32 v82, v195, v82
	v_cvt_f32_u32_e32 v82, v82
	v_cmp_gt_i32_e32 vcc, 0, v195
	s_nop 1
	v_cndmask_b32_e32 v83, v97, v96, vcc
	v_mul_f32_e32 v82, v83, v82
	v_exp_f32_e32 v82, v82
	v_cmp_ne_u32_e32 vcc, v134, v175
	s_nop 1
	v_cndmask_b32_e32 v82, 2.0, v82, vcc
	v_mul_f32_e32 v66, v82, v66
	v_sub_u32_e32 v82, 0, v193
	v_max_i32_e32 v82, v193, v82
	v_cvt_f32_u32_e32 v82, v82
	v_cmp_gt_i32_e32 vcc, 0, v193
	s_nop 1
	v_cndmask_b32_e32 v83, v97, v96, vcc
	v_mul_f32_e32 v82, v83, v82
	v_exp_f32_e32 v82, v82
	v_cmp_ne_u32_e32 vcc, v134, v173
	s_nop 1
	v_cndmask_b32_e32 v82, 2.0, v82, vcc
	v_mul_f32_e32 v67, v82, v67
	v_sub_u32_e32 v82, 0, v174
	v_max_i32_e32 v82, v174, v82
	v_cvt_f32_u32_e32 v82, v82
	v_cmp_gt_i32_e32 vcc, 0, v174
	s_nop 1
	v_cndmask_b32_e32 v83, v97, v96, vcc
	v_mul_f32_e32 v82, v83, v82
	v_exp_f32_e32 v82, v82
	v_cmp_ne_u32_e32 vcc, v134, v171
	s_nop 1
	v_cndmask_b32_e32 v82, 2.0, v82, vcc
	v_mul_f32_e32 v68, v82, v68
	v_sub_u32_e32 v82, 0, v172
	v_max_i32_e32 v82, v172, v82
	v_cvt_f32_u32_e32 v82, v82
	v_cmp_gt_i32_e32 vcc, 0, v172
	s_nop 1
	v_cndmask_b32_e32 v83, v97, v96, vcc
	v_mul_f32_e32 v82, v83, v82
	v_exp_f32_e32 v82, v82
	v_cmp_ne_u32_e32 vcc, v134, v169
	s_nop 1
	v_cndmask_b32_e32 v82, 2.0, v82, vcc
	v_mul_f32_e32 v69, v82, v69
	v_sub_u32_e32 v82, 0, v170
	v_max_i32_e32 v82, v170, v82
	v_cvt_f32_u32_e32 v82, v82
	v_cmp_gt_i32_e32 vcc, 0, v170
	s_nop 1
	v_cndmask_b32_e32 v83, v97, v96, vcc
	v_mul_f32_e32 v82, v83, v82
	v_exp_f32_e32 v82, v82
	v_cmp_ne_u32_e32 vcc, v134, v167
	s_nop 1
	v_cndmask_b32_e32 v82, 2.0, v82, vcc
	v_mul_f32_e32 v62, v82, v62
	v_sub_u32_e32 v82, 0, v168
	v_max_i32_e32 v82, v168, v82
	v_cvt_f32_u32_e32 v82, v82
	v_cmp_gt_i32_e32 vcc, 0, v168
	s_nop 1
	v_cndmask_b32_e32 v83, v97, v96, vcc
	v_mul_f32_e32 v82, v83, v82
	v_exp_f32_e32 v82, v82
	v_cmp_ne_u32_e32 vcc, v134, v164
	s_nop 1
	v_cndmask_b32_e32 v82, 2.0, v82, vcc
	v_mul_f32_e32 v63, v82, v63
	v_sub_u32_e32 v82, 0, v166
	v_max_i32_e32 v82, v166, v82
	v_cvt_f32_u32_e32 v82, v82
	v_cmp_gt_i32_e32 vcc, 0, v166
	s_nop 1
	v_cndmask_b32_e32 v83, v97, v96, vcc
	v_mul_f32_e32 v82, v83, v82
	v_exp_f32_e32 v82, v82
	v_cmp_ne_u32_e32 vcc, v134, v163
	s_nop 1
	v_cndmask_b32_e32 v82, 2.0, v82, vcc
	v_mul_f32_e32 v64, v82, v64
	v_sub_u32_e32 v82, 0, v165
	v_max_i32_e32 v82, v165, v82
	v_cvt_f32_u32_e32 v82, v82
	v_cmp_gt_i32_e32 vcc, 0, v165
	s_nop 1
	v_cndmask_b32_e32 v83, v97, v96, vcc
	v_mul_f32_e32 v82, v83, v82
	v_exp_f32_e32 v82, v82
	v_cmp_ne_u32_e32 vcc, v134, v149
	s_nop 1
	v_cndmask_b32_e32 v82, 2.0, v82, vcc
	v_mul_f32_e32 v65, v82, v65
	v_sub_u32_e32 v82, 0, v151
	v_max_i32_e32 v82, v151, v82
	v_cvt_f32_u32_e32 v82, v82
	v_cmp_gt_i32_e32 vcc, 0, v151
	s_nop 1
	v_cndmask_b32_e32 v83, v97, v96, vcc
	v_mul_f32_e32 v82, v83, v82
	v_exp_f32_e32 v82, v82
	v_cmp_ne_u32_e32 vcc, v134, v148
	s_nop 1
	v_cndmask_b32_e32 v82, 2.0, v82, vcc
	v_mul_f32_e32 v58, v82, v58
	v_sub_u32_e32 v82, 0, v150
	v_max_i32_e32 v82, v150, v82
	v_cvt_f32_u32_e32 v82, v82
	v_cmp_gt_i32_e32 vcc, 0, v150
	s_nop 1
	v_cndmask_b32_e32 v83, v97, v96, vcc
	v_mul_f32_e32 v82, v83, v82
	v_exp_f32_e32 v82, v82
	v_cmp_ne_u32_e32 vcc, v134, v146
	s_nop 1
	v_cndmask_b32_e32 v82, 2.0, v82, vcc
	v_mul_f32_e32 v59, v82, v59
	v_sub_u32_e32 v82, v134, v147
	v_sub_u32_e32 v83, 0, v82
	v_cmp_gt_i32_e32 vcc, 0, v82
	v_max_i32_e32 v82, v82, v83
	v_cvt_f32_u32_e32 v82, v82
	v_cndmask_b32_e32 v83, v97, v96, vcc
	v_cmp_ne_u32_e32 vcc, v134, v147
	v_mul_f32_e32 v82, v83, v82
	v_exp_f32_e32 v82, v82
	s_nop 0
	v_cndmask_b32_e32 v82, 2.0, v82, vcc
	v_mul_f32_e32 v60, v82, v60
	v_sub_u32_e32 v82, v134, v145
	v_sub_u32_e32 v83, 0, v82
	v_cmp_gt_i32_e32 vcc, 0, v82
	v_max_i32_e32 v82, v82, v83
	v_cvt_f32_u32_e32 v82, v82
	v_cndmask_b32_e32 v83, v97, v96, vcc
	v_cmp_ne_u32_e32 vcc, v134, v145
	v_mul_f32_e32 v82, v83, v82
	v_exp_f32_e32 v82, v82
	s_nop 0
	v_cndmask_b32_e32 v82, 2.0, v82, vcc
	v_mul_f32_e32 v61, v82, v61
	v_sub_u32_e32 v82, v134, v144
	v_sub_u32_e32 v83, 0, v82
	v_cmp_gt_i32_e32 vcc, 0, v82
	v_max_i32_e32 v82, v82, v83
	v_cvt_f32_u32_e32 v82, v82
	v_cndmask_b32_e32 v83, v97, v96, vcc
	v_cmp_ne_u32_e32 vcc, v134, v144
	v_mul_f32_e32 v82, v83, v82
	v_exp_f32_e32 v82, v82
	s_nop 0
	v_cndmask_b32_e32 v82, 2.0, v82, vcc
	v_mul_f32_e32 v54, v82, v54
	v_sub_u32_e32 v82, v134, v143
	v_sub_u32_e32 v83, 0, v82
	v_cmp_gt_i32_e32 vcc, 0, v82
	v_max_i32_e32 v82, v82, v83
	v_cvt_f32_u32_e32 v82, v82
	v_cndmask_b32_e32 v83, v97, v96, vcc
	v_cmp_ne_u32_e32 vcc, v134, v143
	v_mul_f32_e32 v82, v83, v82
	v_exp_f32_e32 v82, v82
	s_nop 0
	v_cndmask_b32_e32 v82, 2.0, v82, vcc
	v_mul_f32_e32 v55, v82, v55
	v_sub_u32_e32 v82, v134, v142
	v_sub_u32_e32 v83, 0, v82
	v_cmp_gt_i32_e32 vcc, 0, v82
	v_max_i32_e32 v82, v82, v83
	v_cvt_f32_u32_e32 v82, v82
	v_cndmask_b32_e32 v83, v97, v96, vcc
	v_cmp_ne_u32_e32 vcc, v134, v142
	v_mul_f32_e32 v82, v83, v82
	v_exp_f32_e32 v82, v82
	s_nop 0
	v_cndmask_b32_e32 v82, 2.0, v82, vcc
	v_mul_f32_e32 v56, v82, v56
	v_sub_u32_e32 v82, v134, v133
	v_sub_u32_e32 v83, 0, v82
	v_cmp_gt_i32_e32 vcc, 0, v82
	v_max_i32_e32 v82, v82, v83
	v_cvt_f32_u32_e32 v82, v82
	v_cndmask_b32_e32 v83, v97, v96, vcc
	v_cmp_ne_u32_e32 vcc, v134, v133
	v_mul_f32_e32 v82, v83, v82
	v_exp_f32_e32 v82, v82
	s_nop 0
	v_cndmask_b32_e32 v82, 2.0, v82, vcc
	v_mul_f32_e32 v57, v82, v57
	v_sub_u32_e32 v82, v134, v132
	v_sub_u32_e32 v83, 0, v82
	v_cmp_gt_i32_e32 vcc, 0, v82
	v_max_i32_e32 v82, v82, v83
	v_cvt_f32_u32_e32 v82, v82
	v_cndmask_b32_e32 v83, v97, v96, vcc
	v_cmp_ne_u32_e32 vcc, v134, v132
	v_mul_f32_e32 v82, v83, v82
	v_exp_f32_e32 v82, v82
	s_nop 0
	v_cndmask_b32_e32 v82, 2.0, v82, vcc
	v_mul_f32_e32 v102, v82, v50
	v_sub_u32_e32 v50, v134, v131
	v_sub_u32_e32 v82, 0, v50
	v_cmp_gt_i32_e32 vcc, 0, v50
	v_max_i32_e32 v50, v50, v82
	v_cvt_f32_u32_e32 v50, v50
	v_cndmask_b32_e32 v82, v97, v96, vcc
	v_cmp_ne_u32_e32 vcc, v134, v131
	v_mul_f32_e32 v50, v82, v50
	v_exp_f32_e32 v50, v50
	s_nop 0
	v_cndmask_b32_e32 v50, 2.0, v50, vcc
	v_mul_f32_e32 v103, v50, v51
	v_sub_u32_e32 v50, v134, v130
	v_sub_u32_e32 v51, 0, v50
	v_cmp_gt_i32_e32 vcc, 0, v50
	v_max_i32_e32 v50, v50, v51
	v_cvt_f32_u32_e32 v50, v50
	v_cndmask_b32_e32 v51, v97, v96, vcc
	v_cmp_ne_u32_e32 vcc, v134, v130
	v_mul_f32_e32 v50, v51, v50
	v_exp_f32_e32 v50, v50
	s_nop 0
	v_cndmask_b32_e32 v50, 2.0, v50, vcc
	v_mul_f32_e32 v104, v50, v52
	v_sub_u32_e32 v50, v134, v129
	v_sub_u32_e32 v51, 0, v50
	v_cmp_gt_i32_e32 vcc, 0, v50
	v_max_i32_e32 v50, v50, v51
	v_cvt_f32_u32_e32 v50, v50
	v_cndmask_b32_e32 v51, v97, v96, vcc
	v_cmp_ne_u32_e32 vcc, v134, v129
	v_mul_f32_e32 v50, v51, v50
	v_exp_f32_e32 v50, v50
	s_nop 0
	v_cndmask_b32_e32 v50, 2.0, v50, vcc
	v_mul_f32_e32 v105, v50, v53
	v_cvt_pk_bf16_f32 v50, v74, v75
	v_cvt_pk_bf16_f32 v51, v76, v77
	v_cvt_pk_bf16_f32 v52, v78, v79
	v_cvt_pk_bf16_f32 v53, v80, v81
	ds_read_b64_tr_b16 v[76:77], v128 offset:20736
	ds_read_b64_tr_b16 v[74:75], v128 offset:18432
	ds_read_b64_tr_b16 v[78:79], v128 offset:18464
	ds_read_b64_tr_b16 v[80:81], v128 offset:20768
	ds_read_b64_tr_b16 v[82:83], v128 offset:18496
	ds_read_b64_tr_b16 v[84:85], v128 offset:20800
	ds_read_b64_tr_b16 v[98:99], v128 offset:18528
	ds_read_b64_tr_b16 v[100:101], v128 offset:20832
	s_waitcnt lgkmcnt(6)
	v_mfma_f32_16x16x32_bf16 v[74:77], v[74:77], v[50:53], 0
	v_cvt_pk_bf16_f32 v70, v70, v71
	v_cvt_pk_bf16_f32 v71, v72, v73
	v_cvt_pk_bf16_f32 v72, v66, v67
	s_waitcnt lgkmcnt(4)
	v_mfma_f32_16x16x32_bf16 v[78:81], v[78:81], v[50:53], 0
	v_cvt_pk_bf16_f32 v73, v68, v69
	s_waitcnt lgkmcnt(2)
	v_mfma_f32_16x16x32_bf16 v[82:85], v[82:85], v[50:53], 0
	s_waitcnt lgkmcnt(0)
	v_mfma_f32_16x16x32_bf16 v[50:53], v[98:101], v[50:53], 0
	ds_read_b64_tr_b16 v[68:69], v128 offset:25344
	ds_read_b64_tr_b16 v[66:67], v128 offset:23040
	ds_read_b64_tr_b16 v[98:99], v128 offset:23072
	ds_read_b64_tr_b16 v[100:101], v128 offset:25376
	s_waitcnt lgkmcnt(2)
	v_mfma_f32_16x16x32_bf16 v[66:69], v[66:69], v[70:73], v[74:77]
	s_waitcnt lgkmcnt(0)
	v_mfma_f32_16x16x32_bf16 v[74:77], v[98:101], v[70:73], v[78:81]
	s_nop 2
	ds_read_b64_tr_b16 v[78:79], v128 offset:23104
	ds_read_b64_tr_b16 v[80:81], v128 offset:25408
	s_waitcnt lgkmcnt(0)
	v_mfma_f32_16x16x32_bf16 v[78:81], v[78:81], v[70:73], v[82:85]
	s_nop 2
	ds_read_b64_tr_b16 v[82:83], v128 offset:23136
	ds_read_b64_tr_b16 v[84:85], v128 offset:25440
	v_cvt_pk_bf16_f32 v62, v62, v63
	v_cvt_pk_bf16_f32 v63, v64, v65
	s_waitcnt lgkmcnt(0)
	v_mfma_f32_16x16x32_bf16 v[50:53], v[82:85], v[70:73], v[50:53]
	v_cvt_pk_bf16_f32 v64, v58, v59
	v_cvt_pk_bf16_f32 v65, v60, v61
	ds_read_b64_tr_b16 v[60:61], v128 offset:29952
	ds_read_b64_tr_b16 v[58:59], v128 offset:27648
	ds_read_b64_tr_b16 v[70:71], v128 offset:27680
	ds_read_b64_tr_b16 v[72:73], v128 offset:29984
	s_waitcnt lgkmcnt(2)
	v_mfma_f32_16x16x32_bf16 v[58:61], v[58:61], v[62:65], v[66:69]
	s_waitcnt lgkmcnt(0)
	v_mfma_f32_16x16x32_bf16 v[66:69], v[70:73], v[62:65], v[74:77]
	ds_read_b64_tr_b16 v[70:71], v128 offset:27712
	ds_read_b64_tr_b16 v[72:73], v128 offset:30016
	s_nop 0
	ds_read_b64_tr_b16 v[74:75], v128 offset:27744
	ds_read_b64_tr_b16 v[76:77], v128 offset:30048
	v_cvt_pk_bf16_f32 v54, v54, v55
	s_waitcnt lgkmcnt(2)
	v_mfma_f32_16x16x32_bf16 v[70:73], v[70:73], v[62:65], v[78:81]
	v_cvt_pk_bf16_f32 v55, v56, v57
	v_cvt_pk_bf16_f32 v56, v102, v103
	v_cvt_pk_bf16_f32 v57, v104, v105
	s_waitcnt lgkmcnt(0)
	v_mfma_f32_16x16x32_bf16 v[50:53], v[74:77], v[62:65], v[50:53]
	ds_read_b64_tr_b16 v[64:65], v128 offset:34560
	ds_read_b64_tr_b16 v[62:63], v128 offset:32256
	ds_read_b64_tr_b16 v[74:75], v128 offset:32288
	ds_read_b64_tr_b16 v[76:77], v128 offset:34592
	s_waitcnt lgkmcnt(2)
	v_mfma_f32_16x16x32_bf16 v[58:61], v[62:65], v[54:57], v[58:61]
	s_waitcnt lgkmcnt(0)
	v_mfma_f32_16x16x32_bf16 v[62:65], v[74:77], v[54:57], v[66:69]
	s_nop 2
	ds_read_b64_tr_b16 v[66:67], v128 offset:32320
	ds_read_b64_tr_b16 v[68:69], v128 offset:34624
	s_waitcnt lgkmcnt(0)
	v_mfma_f32_16x16x32_bf16 v[66:69], v[66:69], v[54:57], v[70:73]
	s_nop 2
	ds_read_b64_tr_b16 v[70:71], v128 offset:32352
	ds_read_b64_tr_b16 v[72:73], v128 offset:34656
	s_waitcnt lgkmcnt(0)
	v_mfma_f32_16x16x32_bf16 v[50:53], v[70:73], v[54:57], v[50:53]
	v_mul_f32_e32 v54, v97, v139
	v_exp_f32_e32 v54, v54
	v_mul_f32_e32 v55, v96, v141
	v_exp_f32_e32 v56, v55
	v_pk_fma_f32 v[8:9], v[54:55], v[8:9], v[60:61] op_sel_hi:[0,1,1]
	v_pk_fma_f32 v[6:7], v[54:55], v[6:7], v[58:59] op_sel_hi:[0,1,1]
	v_pk_fma_f32 v[4:5], v[56:57], v[4:5], v[8:9] op_sel_hi:[0,1,1]
	v_pk_fma_f32 v[2:3], v[56:57], v[2:3], v[6:7] op_sel_hi:[0,1,1]
	v_add_f32_e32 v6, v2, v3
	v_add_f32_e32 v7, v4, v5
	v_add_f32_e32 v6, v6, v7
	v_add_f32_e32 v55, 0, v6
	v_pk_fma_f32 v[6:7], v[54:55], v[16:17], v[64:65] op_sel_hi:[0,1,1]
	v_pk_fma_f32 v[8:9], v[54:55], v[14:15], v[62:63] op_sel_hi:[0,1,1]
	v_pk_fma_f32 v[6:7], v[56:57], v[12:13], v[6:7] op_sel_hi:[0,1,1]
	v_pk_fma_f32 v[8:9], v[56:57], v[10:11], v[8:9] op_sel_hi:[0,1,1]
	v_add_f32_e32 v10, v8, v9
	v_add_f32_e32 v11, v6, v7
	v_add_f32_e32 v10, v10, v11
	v_add_f32_e32 v14, v55, v10
	v_pk_fma_f32 v[10:11], v[54:55], v[40:41], v[68:69] op_sel_hi:[0,1,1]
	v_pk_fma_f32 v[12:13], v[54:55], v[38:39], v[66:67] op_sel_hi:[0,1,1]
	v_pk_fma_f32 v[10:11], v[56:57], v[36:37], v[10:11] op_sel_hi:[0,1,1]
	v_pk_fma_f32 v[12:13], v[56:57], v[34:35], v[12:13] op_sel_hi:[0,1,1]
	v_add_f32_e32 v15, v12, v13
	v_add_f32_e32 v16, v10, v11
	v_add_f32_e32 v15, v15, v16
	v_add_f32_e32 v34, v14, v15
	v_pk_fma_f32 v[14:15], v[54:55], v[44:45], v[52:53] op_sel_hi:[0,1,1]
	v_pk_fma_f32 v[16:17], v[54:55], v[42:43], v[50:51] op_sel_hi:[0,1,1]
	v_pk_fma_f32 v[14:15], v[56:57], v[48:49], v[14:15] op_sel_hi:[0,1,1]
	v_pk_fma_f32 v[16:17], v[56:57], v[46:47], v[16:17] op_sel_hi:[0,1,1]
	v_add_f32_e32 v35, v16, v17
	v_add_f32_e32 v36, v14, v15
	v_add_f32_e32 v35, v35, v36
	v_add_f32_e32 v34, v34, v35
	v_mov_b32_e32 v35, v34
	s_nop 1
	v_permlane16_swap_b32_e32 v34, v35
	v_add_f32_e32 v34, v34, v35
	v_mov_b32_e32 v35, v34
	s_nop 1
	v_permlane32_swap_b32_e32 v34, v35
	v_add_f32_e32 v34, v34, v35
	v_fmac_f32_e32 v5, 0xbc800000, v34
	v_fmac_f32_e32 v3, 0xbc800000, v34
	v_fmamk_f32 v4, v34, 0xbc800000, v4
	v_fmamk_f32 v2, v34, 0xbc800000, v2
	v_mul_f32_e32 v35, v3, v3
	v_mul_f32_e32 v36, v5, v5
	v_fmac_f32_e32 v35, v2, v2
	v_fmac_f32_e32 v36, v4, v4
	v_fmac_f32_e32 v7, 0xbc800000, v34
	v_fmac_f32_e32 v9, 0xbc800000, v34
	v_add_f32_e32 v35, v35, v36
	v_fmamk_f32 v6, v34, 0xbc800000, v6
	v_fmamk_f32 v8, v34, 0xbc800000, v8
	v_mul_f32_e32 v36, v9, v9
	v_mul_f32_e32 v37, v7, v7
	v_fmac_f32_e32 v36, v8, v8
	v_fmac_f32_e32 v37, v6, v6
	v_add_f32_e32 v36, v36, v37
	v_fmac_f32_e32 v11, 0xbc800000, v34
	v_fmac_f32_e32 v13, 0xbc800000, v34
	v_add_f32_e32 v35, v35, v36
	v_fmamk_f32 v10, v34, 0xbc800000, v10
	v_fmamk_f32 v12, v34, 0xbc800000, v12
	v_mul_f32_e32 v36, v13, v13
	v_mul_f32_e32 v37, v11, v11
	v_fmac_f32_e32 v36, v12, v12
	v_fmac_f32_e32 v37, v10, v10
	v_add_f32_e32 v36, v36, v37
	v_fmac_f32_e32 v15, 0xbc800000, v34
	v_fmac_f32_e32 v17, 0xbc800000, v34
	v_add_f32_e32 v35, v36, v35
	v_fmamk_f32 v14, v34, 0xbc800000, v14
	v_fmamk_f32 v16, v34, 0xbc800000, v16
	v_mul_f32_e32 v34, v17, v17
	v_mul_f32_e32 v36, v15, v15
	v_fmac_f32_e32 v34, v16, v16
	v_fmac_f32_e32 v36, v14, v14
	v_add_f32_e32 v34, v34, v36
	v_add_f32_e32 v34, v34, v35
	v_mov_b32_e32 v35, v34
	s_nop 1
	v_permlane16_swap_b32_e32 v34, v35
	v_add_f32_e32 v34, v34, v35
	v_mov_b32_e32 v35, v34
	s_nop 1
	v_permlane32_swap_b32_e32 v34, v35
	v_add_f32_e32 v34, v34, v35
	v_fmamk_f32 v34, v34, 0x3c800000, v177
	v_rsq_f32_e32 v34, v34
	v_lshlrev_b64 v[36:37], 11, v[86:87]
	s_waitcnt vmcnt(7)
	v_lshlrev_b32_e32 v38, 16, v94
	v_and_b32_e32 v39, 0xffff0000, v94
	v_pk_mul_f32 v[4:5], v[4:5], v[34:35] op_sel_hi:[1,0]
	v_pk_mul_f32 v[2:3], v[2:3], v[34:35] op_sel_hi:[1,0]
	v_lshlrev_b32_e32 v40, 16, v95
	v_and_b32_e32 v41, 0xffff0000, v95
	s_waitcnt vmcnt(6)
	v_pk_mul_f32 v[2:3], v[30:31], v[2:3]
	v_pk_mul_f32 v[4:5], v[32:33], v[4:5]
	v_lshl_add_u64 v[36:37], s[70:71], 0, v[36:37]
	v_pk_mul_f32 v[4:5], v[4:5], v[40:41]
	v_pk_mul_f32 v[2:3], v[2:3], v[38:39]
	v_pk_mul_f32 v[8:9], v[8:9], v[34:35] op_sel_hi:[1,0]
	v_cvt_pk_bf16_f32 v2, v2, v3
	v_cvt_pk_bf16_f32 v3, v4, v5
	v_lshl_add_u64 v[4:5], v[36:37], 0, v[0:1]
	global_store_dwordx2 v[4:5], v[2:3], off
	s_waitcnt vmcnt(6)
	v_lshlrev_b32_e32 v2, 16, v92
	v_and_b32_e32 v3, 0xffff0000, v92
	v_pk_mul_f32 v[6:7], v[6:7], v[34:35] op_sel_hi:[1,0]
	s_waitcnt vmcnt(5)
	v_pk_mul_f32 v[8:9], v[26:27], v[8:9]
	v_lshlrev_b32_e32 v30, 16, v93
	v_and_b32_e32 v31, 0xffff0000, v93
	v_pk_mul_f32 v[6:7], v[28:29], v[6:7]
	v_pk_mul_f32 v[2:3], v[8:9], v[2:3]
	v_pk_mul_f32 v[6:7], v[6:7], v[30:31]
	v_cvt_pk_bf16_f32 v2, v2, v3
	v_pk_mul_f32 v[8:9], v[10:11], v[34:35] op_sel_hi:[1,0]
	v_cvt_pk_bf16_f32 v3, v6, v7
	v_pk_mul_f32 v[10:11], v[12:13], v[34:35] op_sel_hi:[1,0]
	global_store_dwordx2 v[4:5], v[2:3], off offset:32
	s_waitcnt vmcnt(5)
	v_lshlrev_b32_e32 v2, 16, v90
	v_and_b32_e32 v3, 0xffff0000, v90
	s_waitcnt vmcnt(4)
	v_pk_mul_f32 v[10:11], v[22:23], v[10:11]
	v_lshlrev_b32_e32 v6, 16, v91
	v_and_b32_e32 v7, 0xffff0000, v91
	v_pk_mul_f32 v[8:9], v[24:25], v[8:9]
	v_pk_mul_f32 v[2:3], v[10:11], v[2:3]
	v_pk_mul_f32 v[6:7], v[8:9], v[6:7]
	v_cvt_pk_bf16_f32 v2, v2, v3
	v_pk_mul_f32 v[10:11], v[16:17], v[34:35] op_sel_hi:[1,0]
	v_cvt_pk_bf16_f32 v3, v6, v7
	global_store_dwordx2 v[4:5], v[2:3], off offset:64
	s_waitcnt vmcnt(4)
	v_lshlrev_b32_e32 v2, 16, v88
	v_and_b32_e32 v3, 0xffff0000, v88
	v_pk_mul_f32 v[8:9], v[14:15], v[34:35] op_sel_hi:[1,0]
	s_waitcnt vmcnt(3)
	v_pk_mul_f32 v[10:11], v[18:19], v[10:11]
	v_lshlrev_b32_e32 v6, 16, v89
	v_and_b32_e32 v7, 0xffff0000, v89
	v_pk_mul_f32 v[8:9], v[20:21], v[8:9]
	v_pk_mul_f32 v[2:3], v[10:11], v[2:3]
	v_pk_mul_f32 v[6:7], v[8:9], v[6:7]
	v_cvt_pk_bf16_f32 v2, v2, v3
	s_nop 0
	v_cvt_pk_bf16_f32 v3, v6, v7
	global_store_dwordx2 v[4:5], v[2:3], off offset:96
	s_barrier
